# v8
# speedup vs baseline: 1.0017x; 1.0017x over previous
; __device__ __forceinline__ float bf2f(unsigned h) { return __uint_as_float(h << 16); }
; __device__ __forceinline__ unsigned pk2(float lo, float hi) { return pg8::cvt_pk_bf16(lo, hi); }
; __device__ __forceinline__ float silu_(float x) { return x * __builtin_amdgcn_rcpf(1.0f + __expf(-x)); }
; __device__ __forceinline__ void b3_gla_item(const Ctx& C, int li, int b, int c, int h) {
;     ...
;     { bf16* Y = (bf16*)(C.ws + WS_XN); const float* ng = C.in[12] + (size_t)li * 256;
; #pragma unroll
;       for (int i = 0; i < 4; ++i) { float tot = 0.f;
; #pragma unroll
;           for (int k = 0; k < 8; ++k) tot += SSQ[k * 64 + 16 * i + fr];
;           const float rstd = rsqrtf(tot * (1.0f / 256.0f) + EPS);
; #pragma unroll
;           for (int j = 0; j < 2; ++j) { const int v = 32 * w + 16 * j + 4 * fq; const f32x4 gn = *(const f32x4*)(ng + v);
;               const v2u gg = *(const v2u*)(PROJ + (size_t)(row0 + 16 * i + fr) * LDP + C_G + h * 256 + v);
;               f32x4 y = acc[i][j] * rstd * gn;
;               y[0] *= silu_(bf2f(gg.x & 0xffffu)); y[1] *= silu_(__uint_as_float(gg.x & 0xffff0000u)); y[2] *= silu_(bf2f(gg.y & 0xffffu)); y[3] *= silu_(__uint_as_float(gg.y & 0xffff0000u));
;               *(v2u*)(Y + (size_t)(row0 + 16 * i + fr) * D + 1024 + h * 256 + v) = (v2u){pk2(y[0], y[1]), pk2(y[2], y[3])}; } } }
.LBB0_651:
	s_or_b64 exec, exec, s[6:7]
	v_or_b32_e32 v32, s10, v32
	v_or_b32_e32 v36, s20, v37
	v_mov_b64_e32 v[38:39], s[16:17]
	v_ashrrev_i32_e32 v33, 31, v32
	s_waitcnt lgkmcnt(0)
	v_mad_i64_i32 v[34:35], s[6:7], v36, s55, v[38:39]
	s_lshl_b32 s26, s26, 1
	v_lshl_add_u64 v[40:41], v[34:35], 0, s[26:27]
	v_lshlrev_b64 v[34:35], 1, v[32:33]
	v_lshl_add_u64 v[46:47], v[40:41], 0, v[34:35]
	v_add_co_u32_e32 v40, vcc, s66, v46
	s_nop 1
	v_addc_co_u32_e32 v41, vcc, 0, v47, vcc
	s_barrier
	global_load_dwordx2 v[48:49], v[40:41], off offset:1024
	s_load_dwordx2 s[6:7], s[58:59], 0x60
	v_lshl_add_u32 v37, v37, 2, 0
	v_add_u32_e32 v70, 0x15400, v37
	v_add_u32_e32 v71, 0x400, v70
	v_mov_b64_e32 v[40:41], s[38:39]
	s_waitcnt lgkmcnt(0)
	v_lshl_add_u64 v[32:33], v[32:33], 2, s[6:7]
	global_load_dwordx4 v[236:239], v[32:33], off
	global_load_dwordx4 v[240:243], v[32:33], off offset:64
	ds_read2_b32 v[50:51], v70 offset1:16
	ds_read2_b32 v[52:53], v70 offset0:64 offset1:80
	ds_read2_b32 v[54:55], v70 offset0:128 offset1:144
	ds_read2_b32 v[56:57], v70 offset0:192 offset1:208
	ds_read2_b32 v[60:61], v71 offset1:16
	ds_read2_b32 v[62:63], v71 offset0:64 offset1:80
	ds_read2_b32 v[64:65], v71 offset0:128 offset1:144
	ds_read2_b32 v[66:67], v71 offset0:192 offset1:208
	s_waitcnt lgkmcnt(7)
	v_mov_b32_e32 v68, v51
	v_mov_b32_e32 v69, v50
	s_waitcnt lgkmcnt(6)
	v_mov_b32_e32 v50, v53
	v_mov_b32_e32 v51, v52
	s_waitcnt lgkmcnt(5)
	v_mov_b32_e32 v52, v55
	v_mov_b32_e32 v53, v54
	s_waitcnt lgkmcnt(4)
	v_mov_b32_e32 v54, v57
	v_mov_b32_e32 v55, v56
	v_pk_add_f32 v[56:57], v[68:69], 0 op_sel_hi:[1,0]
	s_waitcnt lgkmcnt(3)
	v_mov_b32_e32 v68, v61
	v_pk_add_f32 v[50:51], v[56:57], v[50:51]
	v_mov_b32_e32 v69, v60
	v_pk_add_f32 v[50:51], v[50:51], v[52:53]
	s_waitcnt lgkmcnt(2)
	v_mov_b32_e32 v60, v63
	v_pk_add_f32 v[50:51], v[50:51], v[54:55]
	v_mov_b32_e32 v61, v62
	v_pk_add_f32 v[50:51], v[50:51], v[68:69]
	s_waitcnt lgkmcnt(1)
	v_mov_b32_e32 v62, v65
	v_mov_b32_e32 v63, v64
	v_pk_add_f32 v[50:51], v[50:51], v[60:61]
	s_waitcnt lgkmcnt(0)
	v_mov_b32_e32 v64, v67
	v_mov_b32_e32 v65, v66
	v_pk_add_f32 v[50:51], v[50:51], v[62:63]
	v_ashrrev_i32_e32 v37, 31, v36
	v_pk_add_f32 v[50:51], v[50:51], v[64:65]
	v_lshlrev_b64 v[58:59], 12, v[36:37]
	v_pk_fma_f32 v[50:51], v[50:51], s[54:55], v[40:41] op_sel_hi:[1,0,0]
	v_lshl_add_u64 v[58:59], s[56:57], 0, v[58:59]
	v_mul_f32_e32 v37, 0x4b800000, v51
	v_cmp_gt_f32_e32 vcc, s67, v51
	v_lshl_add_u64 v[58:59], v[58:59], 0, s[26:27]
	v_lshl_add_u64 v[52:53], v[58:59], 0, v[34:35]
	v_cndmask_b32_e32 v37, v51, v37, vcc
	v_rsq_f32_e32 v37, v37
	v_lshl_add_u64 v[46:47], v[46:47], 0, s[42:43]
	global_load_dwordx2 v[46:47], v[46:47], off offset:32
	v_mul_f32_e32 v51, 0x45800000, v37
	v_cndmask_b32_e32 v54, v37, v51, vcc
	v_pk_mul_f32 v[28:29], v[28:29], v[54:55] op_sel_hi:[1,0]
	v_pk_mul_f32 v[30:31], v[30:31], v[54:55] op_sel_hi:[1,0]
	s_waitcnt vmcnt(3)
	v_lshlrev_b32_e32 v56, 16, v48
	v_and_b32_e32 v57, 0xffff0000, v48
	v_lshlrev_b32_e32 v48, 16, v49
	v_and_b32_e32 v49, 0xffff0000, v49
	v_mul_f32_e32 v37, 0xbfb8aa3b, v56
	v_mul_f32_e32 v51, 0xbfb8aa3b, v57
	v_mul_f32_e32 v55, 0xbfb8aa3b, v48
	v_mul_f32_e32 v58, 0xbfb8aa3b, v49
	v_exp_f32_e32 v37, v37
	v_exp_f32_e32 v51, v51
	v_exp_f32_e32 v55, v55
	v_exp_f32_e32 v58, v58
	v_add_f32_e32 v37, 1.0, v37
	v_add_f32_e32 v51, 1.0, v51
	v_add_f32_e32 v55, 1.0, v55
	v_add_f32_e32 v61, 1.0, v58
	v_rcp_f32_e32 v58, v37
	v_rcp_f32_e32 v59, v51
	v_rcp_f32_e32 v60, v55
	v_rcp_f32_e32 v61, v61
	s_waitcnt vmcnt(2)
	v_pk_mul_f32 v[30:31], v[238:239], v[30:31]
	v_pk_mul_f32 v[28:29], v[236:237], v[28:29]
	v_pk_mul_f32 v[42:43], v[58:59], v[56:57]
	v_pk_mul_f32 v[44:45], v[60:61], v[48:49]
	v_pk_mul_f32 v[28:29], v[42:43], v[28:29]
	v_pk_mul_f32 v[30:31], v[44:45], v[30:31]
	v_cvt_pk_bf16_f32 v28, v28, v29
	v_cvt_pk_bf16_f32 v29, v30, v31
	v_add_co_u32_e32 v30, vcc, s87, v52
	v_or_b32_e32 v42, 16, v36
	s_nop 0
	v_addc_co_u32_e32 v31, vcc, 0, v53, vcc
	global_store_dwordx2 v[30:31], v[28:29], off offset:2048
	v_mad_i64_i32 v[44:45], s[6:7], v42, s55, v[38:39]
	v_lshl_add_u64 v[44:45], v[44:45], 0, s[26:27]
	v_lshl_add_u64 v[44:45], v[44:45], 0, v[34:35]
	v_add_co_u32_e32 v48, vcc, s66, v44
	v_lshl_add_u64 v[52:53], v[52:53], 0, s[52:53]
	s_nop 0
	v_addc_co_u32_e32 v49, vcc, 0, v45, vcc
	global_load_dwordx2 v[48:49], v[48:49], off offset:1024
	s_waitcnt vmcnt(2)
	v_lshlrev_b32_e32 v56, 16, v46
	v_and_b32_e32 v57, 0xffff0000, v46
	v_lshlrev_b32_e32 v46, 16, v47
	v_and_b32_e32 v47, 0xffff0000, v47
	v_mul_f32_e32 v37, 0xbfb8aa3b, v56
	v_mul_f32_e32 v43, 0xbfb8aa3b, v57
	v_mul_f32_e32 v51, 0xbfb8aa3b, v46
	v_mul_f32_e32 v55, 0xbfb8aa3b, v47
	v_exp_f32_e32 v37, v37
	v_exp_f32_e32 v43, v43
	v_exp_f32_e32 v51, v51
	v_exp_f32_e32 v55, v55
	v_add_f32_e32 v37, 1.0, v37
	v_add_f32_e32 v43, 1.0, v43
	v_add_f32_e32 v51, 1.0, v51
	v_add_f32_e32 v55, 1.0, v55
	v_rcp_f32_e32 v58, v37
	v_rcp_f32_e32 v59, v43
	v_rcp_f32_e32 v60, v51
	v_rcp_f32_e32 v61, v55
	v_pk_mul_f32 v[24:25], v[24:25], v[54:55] op_sel_hi:[1,0]
	v_pk_mul_f32 v[26:27], v[26:27], v[54:55] op_sel_hi:[1,0]
	v_pk_mul_f32 v[54:55], v[58:59], v[56:57]
	v_pk_mul_f32 v[46:47], v[60:61], v[46:47]
	v_mul_f32_e32 v37, 0x4b800000, v50
	v_cmp_gt_f32_e32 vcc, s67, v50
	v_ashrrev_i32_e32 v43, 31, v42
	v_pk_mul_f32 v[26:27], v[242:243], v[26:27]
	v_pk_mul_f32 v[24:25], v[240:241], v[24:25]
	v_pk_mul_f32 v[26:27], v[26:27], v[46:47]
	v_pk_mul_f32 v[24:25], v[24:25], v[54:55]
	v_cndmask_b32_e32 v37, v50, v37, vcc
	v_cvt_pk_bf16_f32 v24, v24, v25
	v_cvt_pk_bf16_f32 v25, v26, v27
	global_store_dwordx2 v[52:53], v[24:25], off offset:32
	v_rsq_f32_e32 v37, v37
	v_lshl_add_u64 v[30:31], v[44:45], 0, s[42:43]
	s_waitcnt vmcnt(1)
; __device__ __forceinline__ float bf2f(unsigned h) { return __uint_as_float(h << 16); }
; __device__ __forceinline__ unsigned pk2(float lo, float hi) { return pg8::cvt_pk_bf16(lo, hi); }
; __device__ __forceinline__ float silu_(float x) { return x * __builtin_amdgcn_rcpf(1.0f + __expf(-x)); }
; __device__ __forceinline__ void b3_gla_item(const Ctx& C, int li, int b, int c, int h) {
;     ...
;       for (int i = 0; i < 4; ++i) { float tot = 0.f;
; #pragma unroll
;           for (int k = 0; k < 8; ++k) tot += SSQ[k * 64 + 16 * i + fr];
;           const float rstd = rsqrtf(tot * (1.0f / 256.0f) + EPS);
; #pragma unroll
;           for (int j = 0; j < 2; ++j) { const int v = 32 * w + 16 * j + 4 * fq; const f32x4 gn = *(const f32x4*)(ng + v);
;               const v2u gg = *(const v2u*)(PROJ + (size_t)(row0 + 16 * i + fr) * LDP + C_G + h * 256 + v);
;               f32x4 y = acc[i][j] * rstd * gn;
;               y[0] *= silu_(bf2f(gg.x & 0xffffu)); y[1] *= silu_(__uint_as_float(gg.x & 0xffff0000u)); y[2] *= silu_(bf2f(gg.y & 0xffffu)); y[3] *= silu_(__uint_as_float(gg.y & 0xffff0000u));
;               *(v2u*)(Y + (size_t)(row0 + 16 * i + fr) * D + 1024 + h * 256 + v) = (v2u){pk2(y[0], y[1]), pk2(y[2], y[3])}; } } }
	v_lshlrev_b32_e32 v46, 16, v48
	v_and_b32_e32 v47, 0xffff0000, v48
	v_mul_f32_e32 v44, 0x45800000, v37
	v_lshlrev_b32_e32 v48, 16, v49
	v_and_b32_e32 v49, 0xffff0000, v49
	v_cndmask_b32_e32 v44, v37, v44, vcc
	v_mul_f32_e32 v37, 0xbfb8aa3b, v46
	v_mul_f32_e32 v45, 0xbfb8aa3b, v47
	v_mul_f32_e32 v50, 0xbfb8aa3b, v48
	v_mul_f32_e32 v51, 0xbfb8aa3b, v49
	v_exp_f32_e32 v37, v37
	v_exp_f32_e32 v45, v45
	v_exp_f32_e32 v50, v50
	v_exp_f32_e32 v51, v51
	global_load_dwordx2 v[30:31], v[30:31], off offset:32
	v_add_f32_e32 v37, 1.0, v37
	v_add_f32_e32 v45, 1.0, v45
	v_add_f32_e32 v52, 1.0, v50
	v_add_f32_e32 v53, 1.0, v51
	v_rcp_f32_e32 v50, v37
	v_rcp_f32_e32 v51, v45
	v_rcp_f32_e32 v52, v52
	v_rcp_f32_e32 v53, v53
	v_lshlrev_b64 v[28:29], 12, v[42:43]
	v_lshl_add_u64 v[28:29], s[56:57], 0, v[28:29]
	v_lshl_add_u64 v[28:29], v[28:29], 0, s[26:27]
	v_pk_mul_f32 v[20:21], v[20:21], v[44:45] op_sel_hi:[1,0]
	v_pk_mul_f32 v[22:23], v[22:23], v[44:45] op_sel_hi:[1,0]
	v_lshl_add_u64 v[28:29], v[28:29], 0, v[34:35]
	v_pk_mul_f32 v[46:47], v[50:51], v[46:47]
	v_pk_mul_f32 v[48:49], v[52:53], v[48:49]
	v_add_co_u32_e64 v42, s[6:7], s87, v28
	v_pk_mul_f32 v[22:23], v[238:239], v[22:23]
	v_pk_mul_f32 v[20:21], v[236:237], v[20:21]
	v_pk_mul_f32 v[22:23], v[48:49], v[22:23]
	v_pk_mul_f32 v[20:21], v[46:47], v[20:21]
	v_addc_co_u32_e64 v43, s[6:7], 0, v29, s[6:7]
	v_cvt_pk_bf16_f32 v20, v20, v21
	v_cvt_pk_bf16_f32 v21, v22, v23
	global_store_dwordx2 v[42:43], v[20:21], off offset:2048
	v_or_b32_e32 v24, 32, v36
	v_mad_i64_i32 v[26:27], s[6:7], v24, s55, v[38:39]
	v_lshl_add_u64 v[26:27], v[26:27], 0, s[26:27]
	v_lshl_add_u64 v[26:27], v[26:27], 0, v[34:35]
	v_add_co_u32_e32 v42, vcc, s66, v26
	s_waitcnt vmcnt(1)
	v_lshlrev_b32_e32 v46, 16, v30
	v_and_b32_e32 v47, 0xffff0000, v30
	v_lshlrev_b32_e32 v30, 16, v31
	v_and_b32_e32 v31, 0xffff0000, v31
	v_mul_f32_e32 v25, 0xbfb8aa3b, v46
	v_mul_f32_e32 v37, 0xbfb8aa3b, v47
	v_mul_f32_e32 v45, 0xbfb8aa3b, v30
	v_mul_f32_e32 v48, 0xbfb8aa3b, v31
	v_exp_f32_e32 v25, v25
	v_exp_f32_e32 v37, v37
	v_exp_f32_e32 v45, v45
	v_exp_f32_e32 v48, v48
	v_addc_co_u32_e32 v43, vcc, 0, v27, vcc
	global_load_dwordx2 v[42:43], v[42:43], off offset:1024
	v_add_f32_e32 v25, 1.0, v25
	v_add_f32_e32 v37, 1.0, v37
	v_add_f32_e32 v45, 1.0, v45
	v_add_f32_e32 v51, 1.0, v48
	v_rcp_f32_e32 v48, v25
	v_rcp_f32_e32 v49, v37
	v_rcp_f32_e32 v50, v45
	v_rcp_f32_e32 v51, v51
	v_pk_mul_f32 v[16:17], v[16:17], v[44:45] op_sel_hi:[1,0]
	v_pk_mul_f32 v[18:19], v[18:19], v[44:45] op_sel_hi:[1,0]
	v_pk_mul_f32 v[44:45], v[48:49], v[46:47]
	v_pk_mul_f32 v[30:31], v[50:51], v[30:31]
	v_lshl_add_u64 v[28:29], v[28:29], 0, s[52:53]
	v_lshl_add_u64 v[26:27], v[26:27], 0, s[42:43]
	v_ashrrev_i32_e32 v25, 31, v24
	v_lshlrev_b64 v[24:25], 12, v[24:25]
	v_lshl_add_u64 v[24:25], s[56:57], 0, v[24:25]
	v_lshl_add_u64 v[24:25], v[24:25], 0, s[26:27]
	v_lshl_add_u64 v[24:25], v[24:25], 0, v[34:35]
	v_pk_mul_f32 v[18:19], v[242:243], v[18:19]
	v_pk_mul_f32 v[16:17], v[240:241], v[16:17]
	v_pk_mul_f32 v[18:19], v[18:19], v[30:31]
	v_pk_mul_f32 v[16:17], v[16:17], v[44:45]
	s_nop 0
	v_cvt_pk_bf16_f32 v16, v16, v17
	v_cvt_pk_bf16_f32 v17, v18, v19
	global_store_dwordx2 v[28:29], v[16:17], off offset:32
	ds_read2_b32 v[20:21], v70 offset0:32 offset1:48
	ds_read2_b32 v[22:23], v70 offset0:96 offset1:112
	ds_read2_b32 v[28:29], v70 offset0:160 offset1:176
	ds_read2_b32 v[30:31], v70 offset0:224 offset1:240
	ds_read2_b32 v[44:45], v71 offset0:32 offset1:48
	ds_read2_b32 v[46:47], v71 offset0:96 offset1:112
	ds_read2_b32 v[48:49], v71 offset0:160 offset1:176
	ds_read2_b32 v[50:51], v71 offset0:224 offset1:240
	s_waitcnt lgkmcnt(7)
	v_mov_b32_e32 v52, v21
	v_mov_b32_e32 v53, v20
	s_waitcnt lgkmcnt(6)
	v_mov_b32_e32 v20, v23
	v_mov_b32_e32 v21, v22
	s_waitcnt lgkmcnt(5)
	v_mov_b32_e32 v22, v29
	v_mov_b32_e32 v23, v28
	s_waitcnt lgkmcnt(4)
	v_mov_b32_e32 v28, v31
	v_mov_b32_e32 v29, v30
	v_pk_add_f32 v[30:31], v[52:53], 0 op_sel_hi:[1,0]
	s_waitcnt lgkmcnt(3)
	v_mov_b32_e32 v52, v45
	v_pk_add_f32 v[20:21], v[30:31], v[20:21]
	v_mov_b32_e32 v53, v44
	v_pk_add_f32 v[20:21], v[20:21], v[22:23]
	s_waitcnt lgkmcnt(2)
	v_mov_b32_e32 v44, v47
	v_pk_add_f32 v[20:21], v[20:21], v[28:29]
	v_mov_b32_e32 v45, v46
	v_pk_add_f32 v[20:21], v[20:21], v[52:53]
	s_waitcnt lgkmcnt(1)
	v_mov_b32_e32 v46, v49
	v_mov_b32_e32 v47, v48
	v_pk_add_f32 v[20:21], v[20:21], v[44:45]
	s_waitcnt lgkmcnt(0)
	v_mov_b32_e32 v48, v51
	v_mov_b32_e32 v49, v50
	v_pk_add_f32 v[20:21], v[20:21], v[46:47]
	s_waitcnt vmcnt(1)
; __device__ __forceinline__ float bf2f(unsigned h) { return __uint_as_float(h << 16); }
; __device__ __forceinline__ unsigned pk2(float lo, float hi) { return pg8::cvt_pk_bf16(lo, hi); }
; __device__ __forceinline__ float silu_(float x) { return x * __builtin_amdgcn_rcpf(1.0f + __expf(-x)); }
; __device__ __forceinline__ void b3_gla_item(const Ctx& C, int li, int b, int c, int h) {
;     ...
;       for (int i = 0; i < 4; ++i) { float tot = 0.f;
; #pragma unroll
;           for (int k = 0; k < 8; ++k) tot += SSQ[k * 64 + 16 * i + fr];
;           const float rstd = rsqrtf(tot * (1.0f / 256.0f) + EPS);
; #pragma unroll
;           for (int j = 0; j < 2; ++j) { const int v = 32 * w + 16 * j + 4 * fq; const f32x4 gn = *(const f32x4*)(ng + v);
;               const v2u gg = *(const v2u*)(PROJ + (size_t)(row0 + 16 * i + fr) * LDP + C_G + h * 256 + v);
;               f32x4 y = acc[i][j] * rstd * gn;
;               y[0] *= silu_(bf2f(gg.x & 0xffffu)); y[1] *= silu_(__uint_as_float(gg.x & 0xffff0000u)); y[2] *= silu_(bf2f(gg.y & 0xffffu)); y[3] *= silu_(__uint_as_float(gg.y & 0xffff0000u));
;               *(v2u*)(Y + (size_t)(row0 + 16 * i + fr) * D + 1024 + h * 256 + v) = (v2u){pk2(y[0], y[1]), pk2(y[2], y[3])}; } } }
	v_lshlrev_b32_e32 v30, 16, v42
	v_pk_add_f32 v[20:21], v[20:21], v[48:49]
	v_and_b32_e32 v31, 0xffff0000, v42
	v_pk_fma_f32 v[20:21], v[20:21], s[54:55], v[40:41] op_sel_hi:[1,0,0]
	v_lshlrev_b32_e32 v40, 16, v43
	v_mul_f32_e32 v22, 0x4b800000, v21
	v_cmp_gt_f32_e32 vcc, s67, v21
	v_and_b32_e32 v41, 0xffff0000, v43
	v_mul_f32_e32 v29, 0xbfb8aa3b, v31
	v_cndmask_b32_e32 v21, v21, v22, vcc
	v_rsq_f32_e32 v21, v21
	v_mul_f32_e32 v37, 0xbfb8aa3b, v40
	v_mul_f32_e32 v42, 0xbfb8aa3b, v41
	v_exp_f32_e32 v29, v29
	v_mul_f32_e32 v28, 0x45800000, v21
	v_cndmask_b32_e32 v28, v21, v28, vcc
	v_mul_f32_e32 v21, 0xbfb8aa3b, v30
	v_exp_f32_e32 v21, v21
	v_exp_f32_e32 v37, v37
	v_exp_f32_e32 v42, v42
	global_load_dwordx2 v[26:27], v[26:27], off offset:32
	v_add_f32_e32 v21, 1.0, v21
	v_add_f32_e32 v29, 1.0, v29
	v_add_f32_e32 v37, 1.0, v37
	v_add_f32_e32 v45, 1.0, v42
	v_rcp_f32_e32 v42, v21
	v_rcp_f32_e32 v43, v29
	v_rcp_f32_e32 v44, v37
	v_rcp_f32_e32 v45, v45
	v_pk_mul_f32 v[12:13], v[12:13], v[28:29] op_sel_hi:[1,0]
	v_pk_mul_f32 v[14:15], v[14:15], v[28:29] op_sel_hi:[1,0]
	v_pk_mul_f32 v[30:31], v[42:43], v[30:31]
	v_pk_mul_f32 v[40:41], v[44:45], v[40:41]
	v_add_co_u32_e64 v22, s[6:7], s87, v24
	v_pk_mul_f32 v[14:15], v[238:239], v[14:15]
	v_pk_mul_f32 v[12:13], v[236:237], v[12:13]
	v_pk_mul_f32 v[14:15], v[40:41], v[14:15]
	v_pk_mul_f32 v[12:13], v[30:31], v[12:13]
	v_addc_co_u32_e64 v23, s[6:7], 0, v25, s[6:7]
	v_cvt_pk_bf16_f32 v12, v12, v13
	v_cvt_pk_bf16_f32 v13, v14, v15
	global_store_dwordx2 v[22:23], v[12:13], off offset:2048
	v_or_b32_e32 v16, 48, v36
	v_mad_i64_i32 v[18:19], s[6:7], v16, s55, v[38:39]
	v_lshl_add_u64 v[18:19], v[18:19], 0, s[26:27]
	v_lshl_add_u64 v[18:19], v[18:19], 0, v[34:35]
	v_add_co_u32_e32 v22, vcc, s66, v18
	v_lshl_add_u64 v[24:25], v[24:25], 0, s[52:53]
	s_nop 0
	v_addc_co_u32_e32 v23, vcc, 0, v19, vcc
	global_load_dwordx2 v[22:23], v[22:23], off offset:1024
	v_cmp_gt_f32_e32 vcc, s67, v20
	s_waitcnt vmcnt(2)
	v_lshlrev_b32_e32 v30, 16, v26
	v_and_b32_e32 v31, 0xffff0000, v26
	v_lshlrev_b32_e32 v26, 16, v27
	v_and_b32_e32 v27, 0xffff0000, v27
	v_mul_f32_e32 v17, 0xbfb8aa3b, v30
	v_mul_f32_e32 v21, 0xbfb8aa3b, v31
	v_mul_f32_e32 v29, 0xbfb8aa3b, v26
	v_mul_f32_e32 v36, 0xbfb8aa3b, v27
	v_exp_f32_e32 v17, v17
	v_exp_f32_e32 v21, v21
	v_exp_f32_e32 v29, v29
	v_exp_f32_e32 v36, v36
	v_add_f32_e32 v17, 1.0, v17
	v_add_f32_e32 v21, 1.0, v21
	v_add_f32_e32 v29, 1.0, v29
	v_add_f32_e32 v39, 1.0, v36
	v_rcp_f32_e32 v36, v17
	v_rcp_f32_e32 v37, v21
	v_rcp_f32_e32 v38, v29
	v_rcp_f32_e32 v39, v39
	v_pk_mul_f32 v[8:9], v[8:9], v[28:29] op_sel_hi:[1,0]
	v_pk_mul_f32 v[10:11], v[10:11], v[28:29] op_sel_hi:[1,0]
	v_pk_mul_f32 v[28:29], v[36:37], v[30:31]
	v_pk_mul_f32 v[26:27], v[38:39], v[26:27]
	v_ashrrev_i32_e32 v17, 31, v16
	v_pk_mul_f32 v[10:11], v[242:243], v[10:11]
	v_pk_mul_f32 v[8:9], v[240:241], v[8:9]
	v_pk_mul_f32 v[10:11], v[10:11], v[26:27]
	v_pk_mul_f32 v[8:9], v[8:9], v[28:29]
	v_lshlrev_b64 v[12:13], 12, v[16:17]
	v_cvt_pk_bf16_f32 v8, v8, v9
	v_cvt_pk_bf16_f32 v9, v10, v11
	global_store_dwordx2 v[24:25], v[8:9], off offset:32
	v_mul_f32_e32 v16, 0x4b800000, v20
	v_cndmask_b32_e32 v16, v20, v16, vcc
	v_lshl_add_u64 v[14:15], v[18:19], 0, s[42:43]
	v_rsq_f32_e32 v18, v16
	global_load_dwordx2 v[14:15], v[14:15], off offset:32
	s_waitcnt vmcnt(2)
	v_lshlrev_b32_e32 v20, 16, v22
	v_and_b32_e32 v21, 0xffff0000, v22
	v_mul_f32_e32 v19, 0x45800000, v18
	v_lshlrev_b32_e32 v22, 16, v23
	v_and_b32_e32 v23, 0xffff0000, v23
	v_cndmask_b32_e32 v18, v18, v19, vcc
	v_mul_f32_e32 v19, 0xbfb8aa3b, v20
	v_mul_f32_e32 v24, 0xbfb8aa3b, v21
	v_mul_f32_e32 v25, 0xbfb8aa3b, v22
	v_mul_f32_e32 v26, 0xbfb8aa3b, v23
	v_exp_f32_e32 v19, v19
	v_exp_f32_e32 v24, v24
	v_exp_f32_e32 v25, v25
	v_exp_f32_e32 v26, v26
	v_add_f32_e32 v19, 1.0, v19
	v_add_f32_e32 v27, 1.0, v24
	v_add_f32_e32 v28, 1.0, v25
	v_add_f32_e32 v29, 1.0, v26
	v_rcp_f32_e32 v24, v19
	v_rcp_f32_e32 v25, v27
	v_rcp_f32_e32 v26, v28
	v_rcp_f32_e32 v27, v29
	v_lshl_add_u64 v[12:13], s[56:57], 0, v[12:13]
	v_lshl_add_u64 v[12:13], v[12:13], 0, s[26:27]
	v_pk_mul_f32 v[4:5], v[4:5], v[18:19] op_sel_hi:[1,0]
	v_pk_mul_f32 v[6:7], v[6:7], v[18:19] op_sel_hi:[1,0]
	v_lshl_add_u64 v[12:13], v[12:13], 0, v[34:35]
	v_pk_mul_f32 v[20:21], v[24:25], v[20:21]
	v_pk_mul_f32 v[22:23], v[26:27], v[22:23]
	v_add_co_u32_e64 v16, s[6:7], s87, v12
	v_pk_mul_f32 v[0:1], v[0:1], v[18:19] op_sel_hi:[1,0]
	s_nop 0
	v_addc_co_u32_e64 v17, s[6:7], 0, v13, s[6:7]
	v_pk_mul_f32 v[2:3], v[2:3], v[18:19] op_sel_hi:[1,0]
	v_pk_mul_f32 v[6:7], v[238:239], v[6:7]
	v_pk_mul_f32 v[4:5], v[236:237], v[4:5]
	v_pk_mul_f32 v[6:7], v[22:23], v[6:7]
	v_pk_mul_f32 v[4:5], v[20:21], v[4:5]
	v_lshl_add_u64 v[8:9], v[12:13], 0, s[52:53]
	v_cvt_pk_bf16_f32 v4, v4, v5
	v_cvt_pk_bf16_f32 v5, v6, v7
	global_store_dwordx2 v[16:17], v[4:5], off offset:2048
	s_waitcnt vmcnt(1)
	v_lshlrev_b32_e32 v10, 16, v14
	v_and_b32_e32 v11, 0xffff0000, v14
	v_lshlrev_b32_e32 v12, 16, v15
	v_and_b32_e32 v13, 0xffff0000, v15
	v_mul_f32_e32 v14, 0xbfb8aa3b, v10
	v_mul_f32_e32 v15, 0xbfb8aa3b, v11
	v_mul_f32_e32 v16, 0xbfb8aa3b, v12
	v_mul_f32_e32 v17, 0xbfb8aa3b, v13
	v_exp_f32_e32 v14, v14
	v_exp_f32_e32 v15, v15
	v_exp_f32_e32 v16, v16
	v_exp_f32_e32 v17, v17
	v_add_f32_e32 v14, 1.0, v14
	v_add_f32_e32 v15, 1.0, v15
	v_add_f32_e32 v16, 1.0, v16
	v_add_f32_e32 v17, 1.0, v17
	v_rcp_f32_e32 v14, v14
	v_rcp_f32_e32 v15, v15
	v_rcp_f32_e32 v16, v16
	v_rcp_f32_e32 v17, v17
	v_pk_mul_f32 v[10:11], v[14:15], v[10:11]
	v_pk_mul_f32 v[12:13], v[16:17], v[12:13]
	v_pk_mul_f32 v[2:3], v[242:243], v[2:3]
	v_pk_mul_f32 v[0:1], v[240:241], v[0:1]
	v_pk_mul_f32 v[2:3], v[2:3], v[12:13]
	v_pk_mul_f32 v[0:1], v[0:1], v[10:11]
	s_nop 0
	v_cvt_pk_bf16_f32 v0, v0, v1
	v_cvt_pk_bf16_f32 v1, v2, v3
	global_store_dwordx2 v[8:9], v[0:1], off offset:32
	s_barrier

; __device__ __forceinline__ unsigned pk2(float lo, float hi) { return pg8::cvt_pk_bf16(lo, hi); }
; __device__ __forceinline__ void b3_ssd_item(const Ctx& C, int li, int b, int c, int g) {
;     ...
;     { bf16* Y = (bf16*)(C.ws + WS_XN); const float* ng = C.in[9] + (size_t)li * 1024 + h * 64;
; #pragma unroll
;       for (int i = 0; i < 4; ++i) { float tot = 0.f;
; #pragma unroll
;           for (int k = 0; k < 8; ++k) tot += SSQ[k * 64 + 16 * i + fr];
;           const float rstd = rsqrtf(tot * (1.0f / 512.0f) + EPS);
; #pragma unroll
;           for (int j = 0; j < 4; ++j) { const f32x4 gn = *(const f32x4*)(ng + 16 * j + 4 * fq); const f32x4 y = acc[i][j] * rstd * gn;
;               *(v2u*)(Y + (size_t)(row0 + 16 * i + fr) * D + h * 64 + 16 * j + 4 * fq) = (v2u){pk2(y[0], y[1]), pk2(y[2], y[3])}; } } }
.LBB0_802:
	s_or_b64 exec, exec, s[12:13]
	s_waitcnt lgkmcnt(0)
	s_barrier
	s_load_dwordx2 s[6:7], s[58:59], 0x48
	s_lshl_b64 s[12:13], s[10:11], 2
	v_lshlrev_b32_e32 v72, 2, v100
	v_lshl_add_u32 v68, v127, 2, 0
	v_add_u32_e32 v73, 0x22400, v68
	s_waitcnt lgkmcnt(0)
	s_add_u32 s12, s6, s12
	s_addc_u32 s13, s7, s13
	global_load_dwordx4 v[236:239], v72, s[12:13]
	ds_read2_b32 v[68:69], v73 offset1:16
	ds_read2_b32 v[76:77], v73 offset0:64 offset1:80
	ds_read2_b32 v[78:79], v73 offset0:128 offset1:144
	ds_read2_b32 v[80:81], v73 offset0:192 offset1:208
	v_add_u32_e32 v74, 0x400, v73
	s_waitcnt lgkmcnt(3)
	v_mov_b32_e32 v90, v69
	v_mov_b32_e32 v91, v68
	s_waitcnt lgkmcnt(2)
	v_mov_b32_e32 v68, v77
	v_mov_b32_e32 v69, v76
	s_waitcnt lgkmcnt(1)
	v_mov_b32_e32 v76, v79
	v_mov_b32_e32 v77, v78
	s_waitcnt lgkmcnt(0)
	v_mov_b32_e32 v78, v81
	v_mov_b32_e32 v79, v80
	v_pk_add_f32 v[80:81], v[90:91], 0 op_sel_hi:[1,0]
	ds_read2_b32 v[82:83], v74 offset1:16
	ds_read2_b32 v[84:85], v74 offset0:64 offset1:80
	ds_read2_b32 v[86:87], v74 offset0:128 offset1:144
	ds_read2_b32 v[88:89], v74 offset0:192 offset1:208
	v_pk_add_f32 v[80:81], v[80:81], v[68:69]
	s_waitcnt lgkmcnt(3)
	v_mov_b32_e32 v90, v83
	v_pk_add_f32 v[76:77], v[80:81], v[76:77]
	v_mov_b32_e32 v91, v82
	v_pk_add_f32 v[76:77], v[76:77], v[78:79]
	s_waitcnt lgkmcnt(2)
	v_mov_b32_e32 v82, v85
	v_mov_b32_e32 v83, v84
	v_pk_add_f32 v[76:77], v[76:77], v[90:91]
	s_waitcnt lgkmcnt(1)
	v_mov_b32_e32 v84, v87
	v_mov_b32_e32 v85, v86
	v_pk_add_f32 v[76:77], v[76:77], v[82:83]
	s_waitcnt lgkmcnt(0)
	v_mov_b32_e32 v86, v89
	v_mov_b32_e32 v87, v88
	v_pk_add_f32 v[76:77], v[76:77], v[84:85]
	v_mov_b64_e32 v[70:71], s[38:39]
	v_pk_add_f32 v[76:77], v[76:77], v[86:87]
	s_lshl_b64 s[6:7], s[10:11], 1
	v_pk_fma_f32 v[76:77], v[76:77], s[36:37], v[70:71] op_sel_hi:[1,0,0]
	s_add_u32 s6, s56, s6
	v_mul_f32_e32 v75, 0x4b800000, v77
	v_cmp_gt_f32_e32 vcc, s67, v77
	s_addc_u32 s7, s57, s7
	v_lshl_add_u64 v[88:89], s[6:7], 0, v[104:105]
	v_cndmask_b32_e32 v75, v77, v75, vcc
	v_rsq_f32_e32 v75, v75
	v_lshlrev_b32_e32 v104, 12, v98
	v_lshl_add_u64 v[68:69], v[88:89], 0, v[104:105]
	v_add_co_u32_e64 v78, s[6:7], s87, v68
	v_mul_f32_e32 v77, 0x45800000, v75
	v_cndmask_b32_e32 v80, v75, v77, vcc
	v_pk_mul_f32 v[8:9], v[8:9], v[80:81] op_sel_hi:[1,0]
	v_pk_mul_f32 v[10:11], v[10:11], v[80:81] op_sel_hi:[1,0]
	v_addc_co_u32_e64 v79, s[6:7], 0, v69, s[6:7]
	v_pk_mul_f32 v[4:5], v[4:5], v[80:81] op_sel_hi:[1,0]
	v_pk_mul_f32 v[6:7], v[6:7], v[80:81] op_sel_hi:[1,0]
	s_mov_b64 s[6:7], 0xe400000
	v_cmp_gt_f32_e32 vcc, s67, v76
	s_mov_b64 s[10:11], 0
	global_load_dwordx4 v[240:243], v72, s[12:13] offset:64
	global_load_dwordx4 v[244:247], v72, s[12:13] offset:128
	global_load_dwordx4 v[248:251], v72, s[12:13] offset:192
	s_waitcnt vmcnt(0)
	v_pk_mul_f32 v[2:3], v[238:239], v[10:11]
	v_pk_mul_f32 v[0:1], v[236:237], v[8:9]
	v_lshl_add_u64 v[8:9], v[68:69], 0, s[6:7]
	v_cvt_pk_bf16_f32 v0, v0, v1
	v_cvt_pk_bf16_f32 v1, v2, v3
	global_store_dwordx2 v[78:79], v[0:1], off
	s_mov_b32 s6, 0xe410000
	v_pk_mul_f32 v[2:3], v[242:243], v[6:7]
	v_pk_mul_f32 v[0:1], v[240:241], v[4:5]
	v_pk_mul_f32 v[4:5], v[16:17], v[80:81] op_sel_hi:[1,0]
	v_cvt_pk_bf16_f32 v0, v0, v1
	v_cvt_pk_bf16_f32 v1, v2, v3
	global_store_dwordx2 v[8:9], v[0:1], off offset:32
	v_pk_mul_f32 v[6:7], v[18:19], v[80:81] op_sel_hi:[1,0]
	v_pk_mul_f32 v[0:1], v[244:245], v[4:5]
	v_pk_mul_f32 v[2:3], v[246:247], v[6:7]
	v_cvt_pk_bf16_f32 v0, v0, v1
	v_cvt_pk_bf16_f32 v1, v2, v3
	global_store_dwordx2 v[8:9], v[0:1], off offset:64
	v_pk_mul_f32 v[4:5], v[20:21], v[80:81] op_sel_hi:[1,0]
	v_pk_mul_f32 v[6:7], v[22:23], v[80:81] op_sel_hi:[1,0]
	v_pk_mul_f32 v[0:1], v[248:249], v[4:5]
	v_pk_mul_f32 v[2:3], v[250:251], v[6:7]
	v_cvt_pk_bf16_f32 v0, v0, v1
	v_cvt_pk_bf16_f32 v1, v2, v3
	global_store_dwordx2 v[8:9], v[0:1], off offset:96
	v_mul_f32_e32 v4, 0x4b800000, v76
	v_cndmask_b32_e32 v4, v76, v4, vcc
	v_rsq_f32_e32 v6, v4
	v_add_co_u32_e64 v4, s[6:7], s6, v68
	v_mul_f32_e32 v7, 0x45800000, v6
	v_cndmask_b32_e32 v6, v6, v7, vcc
	v_pk_mul_f32 v[8:9], v[40:41], v[6:7] op_sel_hi:[1,0]
	v_pk_mul_f32 v[10:11], v[42:43], v[6:7] op_sel_hi:[1,0]
	v_addc_co_u32_e64 v5, s[6:7], 0, v69, s[6:7]
	s_mov_b32 s6, 0xe420000
	v_pk_mul_f32 v[2:3], v[238:239], v[10:11]
	v_pk_mul_f32 v[0:1], v[236:237], v[8:9]
	v_pk_mul_f32 v[8:9], v[36:37], v[6:7] op_sel_hi:[1,0]
	v_cvt_pk_bf16_f32 v0, v0, v1
	v_cvt_pk_bf16_f32 v1, v2, v3
	global_store_dwordx2 v[4:5], v[0:1], off
	v_pk_mul_f32 v[10:11], v[38:39], v[6:7] op_sel_hi:[1,0]
	v_pk_mul_f32 v[0:1], v[240:241], v[8:9]
	v_pk_mul_f32 v[2:3], v[242:243], v[10:11]
	v_cvt_pk_bf16_f32 v0, v0, v1
	v_cvt_pk_bf16_f32 v1, v2, v3
	global_store_dwordx2 v[4:5], v[0:1], off offset:32
	v_pk_mul_f32 v[8:9], v[28:29], v[6:7] op_sel_hi:[1,0]
	v_pk_mul_f32 v[10:11], v[30:31], v[6:7] op_sel_hi:[1,0]
	v_pk_mul_f32 v[0:1], v[244:245], v[8:9]
	v_pk_mul_f32 v[2:3], v[246:247], v[10:11]
	v_cvt_pk_bf16_f32 v0, v0, v1
	v_cvt_pk_bf16_f32 v1, v2, v3
	global_store_dwordx2 v[4:5], v[0:1], off offset:64
	v_pk_mul_f32 v[8:9], v[44:45], v[6:7] op_sel_hi:[1,0]
	v_pk_mul_f32 v[6:7], v[46:47], v[6:7] op_sel_hi:[1,0]
	v_pk_mul_f32 v[0:1], v[248:249], v[8:9]
	v_pk_mul_f32 v[2:3], v[250:251], v[6:7]
	v_cvt_pk_bf16_f32 v0, v0, v1
	v_cvt_pk_bf16_f32 v1, v2, v3
	global_store_dwordx2 v[4:5], v[0:1], off offset:96
	ds_read2_b32 v[4:5], v73 offset0:32 offset1:48
	ds_read2_b32 v[6:7], v73 offset0:96 offset1:112
	ds_read2_b32 v[8:9], v73 offset0:160 offset1:176
	ds_read2_b32 v[10:11], v73 offset0:224 offset1:240
	ds_read2_b32 v[16:17], v74 offset0:32 offset1:48
	ds_read2_b32 v[18:19], v74 offset0:96 offset1:112
	ds_read2_b32 v[20:21], v74 offset0:160 offset1:176
	ds_read2_b32 v[22:23], v74 offset0:224 offset1:240
	s_waitcnt lgkmcnt(7)
; __device__ __forceinline__ unsigned pk2(float lo, float hi) { return pg8::cvt_pk_bf16(lo, hi); }
; __device__ __forceinline__ void b3_ssd_item(const Ctx& C, int li, int b, int c, int g) {
;     ...
;       for (int i = 0; i < 4; ++i) { float tot = 0.f;
; #pragma unroll
;           for (int k = 0; k < 8; ++k) tot += SSQ[k * 64 + 16 * i + fr];
;           const float rstd = rsqrtf(tot * (1.0f / 512.0f) + EPS);
; #pragma unroll
;           for (int j = 0; j < 4; ++j) { const f32x4 gn = *(const f32x4*)(ng + 16 * j + 4 * fq); const f32x4 y = acc[i][j] * rstd * gn;
;               *(v2u*)(Y + (size_t)(row0 + 16 * i + fr) * D + h * 64 + 16 * j + 4 * fq) = (v2u){pk2(y[0], y[1]), pk2(y[2], y[3])}; } } }
	v_mov_b32_e32 v28, v5
	v_mov_b32_e32 v29, v4
	s_waitcnt lgkmcnt(6)
	v_mov_b32_e32 v4, v7
	v_mov_b32_e32 v5, v6
	s_waitcnt lgkmcnt(5)
	v_mov_b32_e32 v6, v9
	v_mov_b32_e32 v7, v8
	s_waitcnt lgkmcnt(4)
	v_mov_b32_e32 v8, v11
	v_mov_b32_e32 v9, v10
	v_pk_add_f32 v[10:11], v[28:29], 0 op_sel_hi:[1,0]
	s_waitcnt lgkmcnt(3)
	v_mov_b32_e32 v28, v17
	v_pk_add_f32 v[4:5], v[10:11], v[4:5]
	v_mov_b32_e32 v29, v16
	v_pk_add_f32 v[4:5], v[4:5], v[6:7]
	s_waitcnt lgkmcnt(2)
	v_mov_b32_e32 v16, v19
	v_pk_add_f32 v[4:5], v[4:5], v[8:9]
	v_mov_b32_e32 v17, v18
	v_pk_add_f32 v[4:5], v[4:5], v[28:29]
	s_waitcnt lgkmcnt(1)
	v_mov_b32_e32 v18, v21
	v_mov_b32_e32 v19, v20
	v_pk_add_f32 v[4:5], v[4:5], v[16:17]
	s_waitcnt lgkmcnt(0)
	v_mov_b32_e32 v20, v23
	v_mov_b32_e32 v21, v22
	v_pk_add_f32 v[4:5], v[4:5], v[18:19]
	s_nop 0
	v_pk_add_f32 v[4:5], v[4:5], v[20:21]
	s_nop 0
	v_pk_fma_f32 v[4:5], v[4:5], s[36:37], v[70:71] op_sel_hi:[1,0,0]
	s_nop 0
	v_mul_f32_e32 v6, 0x4b800000, v5
	v_cmp_gt_f32_e32 vcc, s67, v5
	s_nop 1
	v_cndmask_b32_e32 v5, v5, v6, vcc
	v_rsq_f32_e32 v5, v5
	v_add_co_u32_e64 v6, s[6:7], s6, v68
	v_mul_f32_e32 v8, 0x45800000, v5
	v_cndmask_b32_e32 v8, v5, v8, vcc
	v_pk_mul_f32 v[10:11], v[56:57], v[8:9] op_sel_hi:[1,0]
	v_pk_mul_f32 v[16:17], v[58:59], v[8:9] op_sel_hi:[1,0]
	v_addc_co_u32_e64 v7, s[6:7], 0, v69, s[6:7]
	v_mul_f32_e32 v5, 0x4b800000, v4
	v_cmp_gt_f32_e32 vcc, s67, v4
	s_mov_b32 s6, 0xe430000
	v_pk_mul_f32 v[2:3], v[238:239], v[16:17]
	v_pk_mul_f32 v[0:1], v[236:237], v[10:11]
	v_pk_mul_f32 v[10:11], v[52:53], v[8:9] op_sel_hi:[1,0]
	v_cvt_pk_bf16_f32 v0, v0, v1
	v_cvt_pk_bf16_f32 v1, v2, v3
	global_store_dwordx2 v[6:7], v[0:1], off
	v_pk_mul_f32 v[16:17], v[54:55], v[8:9] op_sel_hi:[1,0]
	v_cndmask_b32_e32 v4, v4, v5, vcc
	v_pk_mul_f32 v[2:3], v[242:243], v[16:17]
	v_pk_mul_f32 v[0:1], v[240:241], v[10:11]
	v_pk_mul_f32 v[10:11], v[48:49], v[8:9] op_sel_hi:[1,0]
	v_cvt_pk_bf16_f32 v0, v0, v1
	v_cvt_pk_bf16_f32 v1, v2, v3
	global_store_dwordx2 v[6:7], v[0:1], off offset:32
	v_pk_mul_f32 v[16:17], v[50:51], v[8:9] op_sel_hi:[1,0]
	v_pk_mul_f32 v[0:1], v[244:245], v[10:11]
	v_pk_mul_f32 v[2:3], v[246:247], v[16:17]
	v_cvt_pk_bf16_f32 v0, v0, v1
	v_cvt_pk_bf16_f32 v1, v2, v3
	global_store_dwordx2 v[6:7], v[0:1], off offset:64
	v_pk_mul_f32 v[10:11], v[60:61], v[8:9] op_sel_hi:[1,0]
	v_pk_mul_f32 v[8:9], v[62:63], v[8:9] op_sel_hi:[1,0]
	v_pk_mul_f32 v[0:1], v[248:249], v[10:11]
	v_pk_mul_f32 v[2:3], v[250:251], v[8:9]
	v_cvt_pk_bf16_f32 v0, v0, v1
	v_cvt_pk_bf16_f32 v1, v2, v3
	global_store_dwordx2 v[6:7], v[0:1], off offset:96
	v_rsq_f32_e32 v6, v4
	v_add_co_u32_e64 v4, s[6:7], s6, v68
	v_mul_f32_e32 v7, 0x45800000, v6
	v_cndmask_b32_e32 v6, v6, v7, vcc
	v_pk_mul_f32 v[8:9], v[32:33], v[6:7] op_sel_hi:[1,0]
	v_pk_mul_f32 v[10:11], v[34:35], v[6:7] op_sel_hi:[1,0]
	v_addc_co_u32_e64 v5, s[6:7], 0, v69, s[6:7]
	v_pk_mul_f32 v[2:3], v[238:239], v[10:11]
	v_pk_mul_f32 v[0:1], v[236:237], v[8:9]
	v_pk_mul_f32 v[8:9], v[24:25], v[6:7] op_sel_hi:[1,0]
	v_cvt_pk_bf16_f32 v0, v0, v1
	v_cvt_pk_bf16_f32 v1, v2, v3
	global_store_dwordx2 v[4:5], v[0:1], off
	v_pk_mul_f32 v[10:11], v[26:27], v[6:7] op_sel_hi:[1,0]
	v_pk_mul_f32 v[0:1], v[240:241], v[8:9]
	v_pk_mul_f32 v[2:3], v[242:243], v[10:11]
	v_cvt_pk_bf16_f32 v0, v0, v1
	v_cvt_pk_bf16_f32 v1, v2, v3
	global_store_dwordx2 v[4:5], v[0:1], off offset:32
	v_pk_mul_f32 v[8:9], v[12:13], v[6:7] op_sel_hi:[1,0]
	v_pk_mul_f32 v[10:11], v[14:15], v[6:7] op_sel_hi:[1,0]
	v_pk_mul_f32 v[0:1], v[244:245], v[8:9]
	v_pk_mul_f32 v[2:3], v[246:247], v[10:11]
	v_cvt_pk_bf16_f32 v0, v0, v1
	v_cvt_pk_bf16_f32 v1, v2, v3
	global_store_dwordx2 v[4:5], v[0:1], off offset:64
	v_pk_mul_f32 v[8:9], v[64:65], v[6:7] op_sel_hi:[1,0]
	v_pk_mul_f32 v[6:7], v[66:67], v[6:7] op_sel_hi:[1,0]
	v_pk_mul_f32 v[0:1], v[248:249], v[8:9]
	v_pk_mul_f32 v[2:3], v[250:251], v[6:7]
	v_cvt_pk_bf16_f32 v0, v0, v1
	v_cvt_pk_bf16_f32 v1, v2, v3
	global_store_dwordx2 v[4:5], v[0:1], off offset:96
	s_barrier

; __device__ __forceinline__ float bf2f(unsigned h) { return __uint_as_float(h << 16); }
; __device__ __forceinline__ unsigned pk2(float lo, float hi) { return pg8::cvt_pk_bf16(lo, hi); }
; __device__ __forceinline__ float silu_(float x) { return x * __builtin_amdgcn_rcpf(1.0f + __expf(-x)); }
; __device__ __forceinline__ void b3_gla_item(const Ctx& C, int li, int b, int c, int h) {
;     ...
;     { bf16* Y = (bf16*)(C.ws + WS_XN); const float* ng = C.in[12] + (size_t)li * 256;
; #pragma unroll
;       for (int i = 0; i < 4; ++i) { float tot = 0.f;
; #pragma unroll
;           for (int k = 0; k < 8; ++k) tot += SSQ[k * 64 + 16 * i + fr];
;           const float rstd = rsqrtf(tot * (1.0f / 256.0f) + EPS);
; #pragma unroll
;           for (int j = 0; j < 2; ++j) { const int v = 32 * w + 16 * j + 4 * fq; const f32x4 gn = *(const f32x4*)(ng + v);
;               const v2u gg = *(const v2u*)(PROJ + (size_t)(row0 + 16 * i + fr) * LDP + C_G + h * 256 + v);
;               f32x4 y = acc[i][j] * rstd * gn;
;               y[0] *= silu_(bf2f(gg.x & 0xffffu)); y[1] *= silu_(__uint_as_float(gg.x & 0xffff0000u)); y[2] *= silu_(bf2f(gg.y & 0xffffu)); y[3] *= silu_(__uint_as_float(gg.y & 0xffff0000u));
;               *(v2u*)(Y + (size_t)(row0 + 16 * i + fr) * D + 1024 + h * 256 + v) = (v2u){pk2(y[0], y[1]), pk2(y[2], y[3])}; } } }
.LBB0_1739:
	s_or_b64 exec, exec, s[8:9]
	v_or_b32_e32 v32, s10, v32
	v_or_b32_e32 v36, s20, v37
	v_mov_b64_e32 v[38:39], s[16:17]
	v_ashrrev_i32_e32 v33, 31, v32
	s_waitcnt lgkmcnt(0)
	v_mad_i64_i32 v[34:35], s[8:9], v36, s49, v[38:39]
	s_lshl_b32 s26, s26, 1
	v_lshl_add_u64 v[40:41], v[34:35], 0, s[26:27]
	v_lshlrev_b64 v[34:35], 1, v[32:33]
	v_lshl_add_u64 v[46:47], v[40:41], 0, v[34:35]
	v_add_co_u32_e32 v40, vcc, s62, v46
	s_nop 1
	v_addc_co_u32_e32 v41, vcc, 0, v47, vcc
	s_barrier
	global_load_dwordx2 v[48:49], v[40:41], off offset:1024
	s_load_dwordx2 s[8:9], s[52:53], 0x60
	v_lshl_add_u32 v37, v37, 2, 0
	v_add_u32_e32 v70, 0x15400, v37
	v_add_u32_e32 v71, 0x400, v70
	v_mov_b64_e32 v[40:41], s[38:39]
	s_waitcnt lgkmcnt(0)
	v_lshl_add_u64 v[32:33], v[32:33], 2, s[8:9]
	global_load_dwordx4 v[236:239], v[32:33], off offset:1024
	global_load_dwordx4 v[240:243], v[32:33], off offset:1088
	ds_read2_b32 v[50:51], v70 offset1:16
	ds_read2_b32 v[52:53], v70 offset0:64 offset1:80
	ds_read2_b32 v[54:55], v70 offset0:128 offset1:144
	ds_read2_b32 v[56:57], v70 offset0:192 offset1:208
	ds_read2_b32 v[60:61], v71 offset1:16
	ds_read2_b32 v[62:63], v71 offset0:64 offset1:80
	ds_read2_b32 v[64:65], v71 offset0:128 offset1:144
	ds_read2_b32 v[66:67], v71 offset0:192 offset1:208
	s_waitcnt lgkmcnt(7)
	v_mov_b32_e32 v68, v51
	v_mov_b32_e32 v69, v50
	s_waitcnt lgkmcnt(6)
	v_mov_b32_e32 v50, v53
	v_mov_b32_e32 v51, v52
	s_waitcnt lgkmcnt(5)
	v_mov_b32_e32 v52, v55
	v_mov_b32_e32 v53, v54
	s_waitcnt lgkmcnt(4)
	v_mov_b32_e32 v54, v57
	v_mov_b32_e32 v55, v56
	v_pk_add_f32 v[56:57], v[68:69], 0 op_sel_hi:[1,0]
	s_waitcnt lgkmcnt(3)
	v_mov_b32_e32 v68, v61
	v_pk_add_f32 v[50:51], v[56:57], v[50:51]
	v_mov_b32_e32 v69, v60
	v_pk_add_f32 v[50:51], v[50:51], v[52:53]
	s_waitcnt lgkmcnt(2)
	v_mov_b32_e32 v60, v63
	v_pk_add_f32 v[50:51], v[50:51], v[54:55]
	v_mov_b32_e32 v61, v62
	v_pk_add_f32 v[50:51], v[50:51], v[68:69]
	s_waitcnt lgkmcnt(1)
	v_mov_b32_e32 v62, v65
	v_mov_b32_e32 v63, v64
	v_pk_add_f32 v[50:51], v[50:51], v[60:61]
	s_waitcnt lgkmcnt(0)
	v_mov_b32_e32 v64, v67
	v_mov_b32_e32 v65, v66
	v_pk_add_f32 v[50:51], v[50:51], v[62:63]
	v_ashrrev_i32_e32 v37, 31, v36
	v_pk_add_f32 v[50:51], v[50:51], v[64:65]
	v_lshlrev_b64 v[58:59], 12, v[36:37]
	v_pk_fma_f32 v[50:51], v[50:51], s[48:49], v[40:41] op_sel_hi:[1,0,0]
	v_lshl_add_u64 v[58:59], s[50:51], 0, v[58:59]
	v_mul_f32_e32 v37, 0x4b800000, v51
	v_cmp_gt_f32_e32 vcc, s63, v51
	v_lshl_add_u64 v[58:59], v[58:59], 0, s[26:27]
	v_lshl_add_u64 v[52:53], v[58:59], 0, v[34:35]
	v_cndmask_b32_e32 v37, v51, v37, vcc
	v_rsq_f32_e32 v37, v37
	v_lshl_add_u64 v[46:47], v[46:47], 0, s[40:41]
	global_load_dwordx2 v[46:47], v[46:47], off offset:32
	v_mul_f32_e32 v51, 0x45800000, v37
	v_cndmask_b32_e32 v54, v37, v51, vcc
	v_pk_mul_f32 v[28:29], v[28:29], v[54:55] op_sel_hi:[1,0]
	v_pk_mul_f32 v[30:31], v[30:31], v[54:55] op_sel_hi:[1,0]
	s_waitcnt vmcnt(3)
	v_lshlrev_b32_e32 v56, 16, v48
	v_and_b32_e32 v57, 0xffff0000, v48
	v_lshlrev_b32_e32 v48, 16, v49
	v_and_b32_e32 v49, 0xffff0000, v49
	v_mul_f32_e32 v37, 0xbfb8aa3b, v56
	v_mul_f32_e32 v51, 0xbfb8aa3b, v57
	v_mul_f32_e32 v55, 0xbfb8aa3b, v48
	v_mul_f32_e32 v58, 0xbfb8aa3b, v49
	v_exp_f32_e32 v37, v37
	v_exp_f32_e32 v51, v51
	v_exp_f32_e32 v55, v55
	v_exp_f32_e32 v58, v58
	v_add_f32_e32 v37, 1.0, v37
	v_add_f32_e32 v51, 1.0, v51
	v_add_f32_e32 v55, 1.0, v55
	v_add_f32_e32 v61, 1.0, v58
	v_rcp_f32_e32 v58, v37
	v_rcp_f32_e32 v59, v51
	v_rcp_f32_e32 v60, v55
	v_rcp_f32_e32 v61, v61
	s_waitcnt vmcnt(2)
	v_pk_mul_f32 v[30:31], v[238:239], v[30:31]
	v_pk_mul_f32 v[28:29], v[236:237], v[28:29]
	v_pk_mul_f32 v[42:43], v[58:59], v[56:57]
	v_pk_mul_f32 v[44:45], v[60:61], v[48:49]
	v_pk_mul_f32 v[28:29], v[42:43], v[28:29]
	v_pk_mul_f32 v[30:31], v[44:45], v[30:31]
	v_cvt_pk_bf16_f32 v28, v28, v29
	v_cvt_pk_bf16_f32 v29, v30, v31
	v_add_co_u32_e32 v30, vcc, s88, v52
	v_or_b32_e32 v42, 16, v36
	s_nop 0
	v_addc_co_u32_e32 v31, vcc, 0, v53, vcc
	global_store_dwordx2 v[30:31], v[28:29], off offset:2048
	v_mad_i64_i32 v[44:45], s[8:9], v42, s49, v[38:39]
	v_lshl_add_u64 v[44:45], v[44:45], 0, s[26:27]
	v_lshl_add_u64 v[44:45], v[44:45], 0, v[34:35]
	v_add_co_u32_e32 v48, vcc, s62, v44
	v_lshl_add_u64 v[52:53], v[52:53], 0, s[42:43]
	s_nop 0
	v_addc_co_u32_e32 v49, vcc, 0, v45, vcc
	global_load_dwordx2 v[48:49], v[48:49], off offset:1024
	s_waitcnt vmcnt(2)
	v_lshlrev_b32_e32 v56, 16, v46
	v_and_b32_e32 v57, 0xffff0000, v46
	v_lshlrev_b32_e32 v46, 16, v47
	v_and_b32_e32 v47, 0xffff0000, v47
	v_mul_f32_e32 v37, 0xbfb8aa3b, v56
	v_mul_f32_e32 v43, 0xbfb8aa3b, v57
	v_mul_f32_e32 v51, 0xbfb8aa3b, v46
	v_mul_f32_e32 v55, 0xbfb8aa3b, v47
	v_exp_f32_e32 v37, v37
	v_exp_f32_e32 v43, v43
	v_exp_f32_e32 v51, v51
	v_exp_f32_e32 v55, v55
	v_add_f32_e32 v37, 1.0, v37
	v_add_f32_e32 v43, 1.0, v43
	v_add_f32_e32 v51, 1.0, v51
	v_add_f32_e32 v55, 1.0, v55
	v_rcp_f32_e32 v58, v37
	v_rcp_f32_e32 v59, v43
	v_rcp_f32_e32 v60, v51
	v_rcp_f32_e32 v61, v55
	v_pk_mul_f32 v[24:25], v[24:25], v[54:55] op_sel_hi:[1,0]
	v_pk_mul_f32 v[26:27], v[26:27], v[54:55] op_sel_hi:[1,0]
	v_pk_mul_f32 v[54:55], v[58:59], v[56:57]
	v_pk_mul_f32 v[46:47], v[60:61], v[46:47]
	v_mul_f32_e32 v37, 0x4b800000, v50
	v_cmp_gt_f32_e32 vcc, s63, v50
	v_ashrrev_i32_e32 v43, 31, v42
	v_pk_mul_f32 v[26:27], v[242:243], v[26:27]
	v_pk_mul_f32 v[24:25], v[240:241], v[24:25]
	v_pk_mul_f32 v[26:27], v[26:27], v[46:47]
	v_pk_mul_f32 v[24:25], v[24:25], v[54:55]
	v_cndmask_b32_e32 v37, v50, v37, vcc
	v_cvt_pk_bf16_f32 v24, v24, v25
	v_cvt_pk_bf16_f32 v25, v26, v27
	global_store_dwordx2 v[52:53], v[24:25], off offset:32
	v_rsq_f32_e32 v37, v37
	v_lshl_add_u64 v[30:31], v[44:45], 0, s[40:41]
	s_waitcnt vmcnt(1)
; __device__ __forceinline__ float bf2f(unsigned h) { return __uint_as_float(h << 16); }
; __device__ __forceinline__ unsigned pk2(float lo, float hi) { return pg8::cvt_pk_bf16(lo, hi); }
; __device__ __forceinline__ float silu_(float x) { return x * __builtin_amdgcn_rcpf(1.0f + __expf(-x)); }
; __device__ __forceinline__ void b3_gla_item(const Ctx& C, int li, int b, int c, int h) {
;     ...
;       for (int i = 0; i < 4; ++i) { float tot = 0.f;
; #pragma unroll
;           for (int k = 0; k < 8; ++k) tot += SSQ[k * 64 + 16 * i + fr];
;           const float rstd = rsqrtf(tot * (1.0f / 256.0f) + EPS);
; #pragma unroll
;           for (int j = 0; j < 2; ++j) { const int v = 32 * w + 16 * j + 4 * fq; const f32x4 gn = *(const f32x4*)(ng + v);
;               const v2u gg = *(const v2u*)(PROJ + (size_t)(row0 + 16 * i + fr) * LDP + C_G + h * 256 + v);
;               f32x4 y = acc[i][j] * rstd * gn;
;               y[0] *= silu_(bf2f(gg.x & 0xffffu)); y[1] *= silu_(__uint_as_float(gg.x & 0xffff0000u)); y[2] *= silu_(bf2f(gg.y & 0xffffu)); y[3] *= silu_(__uint_as_float(gg.y & 0xffff0000u));
;               *(v2u*)(Y + (size_t)(row0 + 16 * i + fr) * D + 1024 + h * 256 + v) = (v2u){pk2(y[0], y[1]), pk2(y[2], y[3])}; } } }
	v_lshlrev_b32_e32 v46, 16, v48
	v_and_b32_e32 v47, 0xffff0000, v48
	v_mul_f32_e32 v44, 0x45800000, v37
	v_lshlrev_b32_e32 v48, 16, v49
	v_and_b32_e32 v49, 0xffff0000, v49
	v_cndmask_b32_e32 v44, v37, v44, vcc
	v_mul_f32_e32 v37, 0xbfb8aa3b, v46
	v_mul_f32_e32 v45, 0xbfb8aa3b, v47
	v_mul_f32_e32 v50, 0xbfb8aa3b, v48
	v_mul_f32_e32 v51, 0xbfb8aa3b, v49
	v_exp_f32_e32 v37, v37
	v_exp_f32_e32 v45, v45
	v_exp_f32_e32 v50, v50
	v_exp_f32_e32 v51, v51
	global_load_dwordx2 v[30:31], v[30:31], off offset:32
	v_add_f32_e32 v37, 1.0, v37
	v_add_f32_e32 v45, 1.0, v45
	v_add_f32_e32 v52, 1.0, v50
	v_add_f32_e32 v53, 1.0, v51
	v_rcp_f32_e32 v50, v37
	v_rcp_f32_e32 v51, v45
	v_rcp_f32_e32 v52, v52
	v_rcp_f32_e32 v53, v53
	v_lshlrev_b64 v[28:29], 12, v[42:43]
	v_lshl_add_u64 v[28:29], s[50:51], 0, v[28:29]
	v_lshl_add_u64 v[28:29], v[28:29], 0, s[26:27]
	v_pk_mul_f32 v[20:21], v[20:21], v[44:45] op_sel_hi:[1,0]
	v_pk_mul_f32 v[22:23], v[22:23], v[44:45] op_sel_hi:[1,0]
	v_lshl_add_u64 v[28:29], v[28:29], 0, v[34:35]
	v_pk_mul_f32 v[46:47], v[50:51], v[46:47]
	v_pk_mul_f32 v[48:49], v[52:53], v[48:49]
	v_add_co_u32_e64 v42, s[8:9], s88, v28
	v_pk_mul_f32 v[22:23], v[238:239], v[22:23]
	v_pk_mul_f32 v[20:21], v[236:237], v[20:21]
	v_pk_mul_f32 v[22:23], v[48:49], v[22:23]
	v_pk_mul_f32 v[20:21], v[46:47], v[20:21]
	v_addc_co_u32_e64 v43, s[8:9], 0, v29, s[8:9]
	v_cvt_pk_bf16_f32 v20, v20, v21
	v_cvt_pk_bf16_f32 v21, v22, v23
	global_store_dwordx2 v[42:43], v[20:21], off offset:2048
	v_or_b32_e32 v24, 32, v36
	v_mad_i64_i32 v[26:27], s[8:9], v24, s49, v[38:39]
	v_lshl_add_u64 v[26:27], v[26:27], 0, s[26:27]
	v_lshl_add_u64 v[26:27], v[26:27], 0, v[34:35]
	v_add_co_u32_e32 v42, vcc, s62, v26
	s_waitcnt vmcnt(1)
	v_lshlrev_b32_e32 v46, 16, v30
	v_and_b32_e32 v47, 0xffff0000, v30
	v_lshlrev_b32_e32 v30, 16, v31
	v_and_b32_e32 v31, 0xffff0000, v31
	v_mul_f32_e32 v25, 0xbfb8aa3b, v46
	v_mul_f32_e32 v37, 0xbfb8aa3b, v47
	v_mul_f32_e32 v45, 0xbfb8aa3b, v30
	v_mul_f32_e32 v48, 0xbfb8aa3b, v31
	v_exp_f32_e32 v25, v25
	v_exp_f32_e32 v37, v37
	v_exp_f32_e32 v45, v45
	v_exp_f32_e32 v48, v48
	v_addc_co_u32_e32 v43, vcc, 0, v27, vcc
	global_load_dwordx2 v[42:43], v[42:43], off offset:1024
	v_add_f32_e32 v25, 1.0, v25
	v_add_f32_e32 v37, 1.0, v37
	v_add_f32_e32 v45, 1.0, v45
	v_add_f32_e32 v51, 1.0, v48
	v_rcp_f32_e32 v48, v25
	v_rcp_f32_e32 v49, v37
	v_rcp_f32_e32 v50, v45
	v_rcp_f32_e32 v51, v51
	v_pk_mul_f32 v[16:17], v[16:17], v[44:45] op_sel_hi:[1,0]
	v_pk_mul_f32 v[18:19], v[18:19], v[44:45] op_sel_hi:[1,0]
	v_pk_mul_f32 v[44:45], v[48:49], v[46:47]
	v_pk_mul_f32 v[30:31], v[50:51], v[30:31]
	v_lshl_add_u64 v[28:29], v[28:29], 0, s[42:43]
	v_lshl_add_u64 v[26:27], v[26:27], 0, s[40:41]
	v_ashrrev_i32_e32 v25, 31, v24
	v_lshlrev_b64 v[24:25], 12, v[24:25]
	v_lshl_add_u64 v[24:25], s[50:51], 0, v[24:25]
	v_lshl_add_u64 v[24:25], v[24:25], 0, s[26:27]
	v_lshl_add_u64 v[24:25], v[24:25], 0, v[34:35]
	v_pk_mul_f32 v[18:19], v[242:243], v[18:19]
	v_pk_mul_f32 v[16:17], v[240:241], v[16:17]
	v_pk_mul_f32 v[18:19], v[18:19], v[30:31]
	v_pk_mul_f32 v[16:17], v[16:17], v[44:45]
	s_nop 0
	v_cvt_pk_bf16_f32 v16, v16, v17
	v_cvt_pk_bf16_f32 v17, v18, v19
	global_store_dwordx2 v[28:29], v[16:17], off offset:32
	ds_read2_b32 v[20:21], v70 offset0:32 offset1:48
	ds_read2_b32 v[22:23], v70 offset0:96 offset1:112
	ds_read2_b32 v[28:29], v70 offset0:160 offset1:176
	ds_read2_b32 v[30:31], v70 offset0:224 offset1:240
	ds_read2_b32 v[44:45], v71 offset0:32 offset1:48
	ds_read2_b32 v[46:47], v71 offset0:96 offset1:112
	ds_read2_b32 v[48:49], v71 offset0:160 offset1:176
	ds_read2_b32 v[50:51], v71 offset0:224 offset1:240
	s_waitcnt lgkmcnt(7)
	v_mov_b32_e32 v52, v21
	v_mov_b32_e32 v53, v20
	s_waitcnt lgkmcnt(6)
	v_mov_b32_e32 v20, v23
	v_mov_b32_e32 v21, v22
	s_waitcnt lgkmcnt(5)
	v_mov_b32_e32 v22, v29
	v_mov_b32_e32 v23, v28
	s_waitcnt lgkmcnt(4)
	v_mov_b32_e32 v28, v31
	v_mov_b32_e32 v29, v30
	v_pk_add_f32 v[30:31], v[52:53], 0 op_sel_hi:[1,0]
	s_waitcnt lgkmcnt(3)
	v_mov_b32_e32 v52, v45
	v_pk_add_f32 v[20:21], v[30:31], v[20:21]
	v_mov_b32_e32 v53, v44
	v_pk_add_f32 v[20:21], v[20:21], v[22:23]
	s_waitcnt lgkmcnt(2)
	v_mov_b32_e32 v44, v47
	v_pk_add_f32 v[20:21], v[20:21], v[28:29]
	v_mov_b32_e32 v45, v46
	v_pk_add_f32 v[20:21], v[20:21], v[52:53]
	s_waitcnt lgkmcnt(1)
	v_mov_b32_e32 v46, v49
	v_mov_b32_e32 v47, v48
	v_pk_add_f32 v[20:21], v[20:21], v[44:45]
	s_waitcnt lgkmcnt(0)
	v_mov_b32_e32 v48, v51
	v_mov_b32_e32 v49, v50
	v_pk_add_f32 v[20:21], v[20:21], v[46:47]
	s_waitcnt vmcnt(1)
; __device__ __forceinline__ float bf2f(unsigned h) { return __uint_as_float(h << 16); }
; __device__ __forceinline__ unsigned pk2(float lo, float hi) { return pg8::cvt_pk_bf16(lo, hi); }
; __device__ __forceinline__ float silu_(float x) { return x * __builtin_amdgcn_rcpf(1.0f + __expf(-x)); }
; __device__ __forceinline__ void b3_gla_item(const Ctx& C, int li, int b, int c, int h) {
;     ...
;       for (int i = 0; i < 4; ++i) { float tot = 0.f;
; #pragma unroll
;           for (int k = 0; k < 8; ++k) tot += SSQ[k * 64 + 16 * i + fr];
;           const float rstd = rsqrtf(tot * (1.0f / 256.0f) + EPS);
; #pragma unroll
;           for (int j = 0; j < 2; ++j) { const int v = 32 * w + 16 * j + 4 * fq; const f32x4 gn = *(const f32x4*)(ng + v);
;               const v2u gg = *(const v2u*)(PROJ + (size_t)(row0 + 16 * i + fr) * LDP + C_G + h * 256 + v);
;               f32x4 y = acc[i][j] * rstd * gn;
;               y[0] *= silu_(bf2f(gg.x & 0xffffu)); y[1] *= silu_(__uint_as_float(gg.x & 0xffff0000u)); y[2] *= silu_(bf2f(gg.y & 0xffffu)); y[3] *= silu_(__uint_as_float(gg.y & 0xffff0000u));
;               *(v2u*)(Y + (size_t)(row0 + 16 * i + fr) * D + 1024 + h * 256 + v) = (v2u){pk2(y[0], y[1]), pk2(y[2], y[3])}; } } }
	v_lshlrev_b32_e32 v30, 16, v42
	v_pk_add_f32 v[20:21], v[20:21], v[48:49]
	v_and_b32_e32 v31, 0xffff0000, v42
	v_pk_fma_f32 v[20:21], v[20:21], s[48:49], v[40:41] op_sel_hi:[1,0,0]
	v_lshlrev_b32_e32 v40, 16, v43
	v_mul_f32_e32 v22, 0x4b800000, v21
	v_cmp_gt_f32_e32 vcc, s63, v21
	v_and_b32_e32 v41, 0xffff0000, v43
	v_mul_f32_e32 v29, 0xbfb8aa3b, v31
	v_cndmask_b32_e32 v21, v21, v22, vcc
	v_rsq_f32_e32 v21, v21
	v_mul_f32_e32 v37, 0xbfb8aa3b, v40
	v_mul_f32_e32 v42, 0xbfb8aa3b, v41
	v_exp_f32_e32 v29, v29
	v_mul_f32_e32 v28, 0x45800000, v21
	v_cndmask_b32_e32 v28, v21, v28, vcc
	v_mul_f32_e32 v21, 0xbfb8aa3b, v30
	v_exp_f32_e32 v21, v21
	v_exp_f32_e32 v37, v37
	v_exp_f32_e32 v42, v42
	global_load_dwordx2 v[26:27], v[26:27], off offset:32
	v_add_f32_e32 v21, 1.0, v21
	v_add_f32_e32 v29, 1.0, v29
	v_add_f32_e32 v37, 1.0, v37
	v_add_f32_e32 v45, 1.0, v42
	v_rcp_f32_e32 v42, v21
	v_rcp_f32_e32 v43, v29
	v_rcp_f32_e32 v44, v37
	v_rcp_f32_e32 v45, v45
	v_pk_mul_f32 v[12:13], v[12:13], v[28:29] op_sel_hi:[1,0]
	v_pk_mul_f32 v[14:15], v[14:15], v[28:29] op_sel_hi:[1,0]
	v_pk_mul_f32 v[30:31], v[42:43], v[30:31]
	v_pk_mul_f32 v[40:41], v[44:45], v[40:41]
	v_add_co_u32_e64 v22, s[8:9], s88, v24
	v_pk_mul_f32 v[14:15], v[238:239], v[14:15]
	v_pk_mul_f32 v[12:13], v[236:237], v[12:13]
	v_pk_mul_f32 v[14:15], v[40:41], v[14:15]
	v_pk_mul_f32 v[12:13], v[30:31], v[12:13]
	v_addc_co_u32_e64 v23, s[8:9], 0, v25, s[8:9]
	v_cvt_pk_bf16_f32 v12, v12, v13
	v_cvt_pk_bf16_f32 v13, v14, v15
	global_store_dwordx2 v[22:23], v[12:13], off offset:2048
	v_or_b32_e32 v16, 48, v36
	v_mad_i64_i32 v[18:19], s[8:9], v16, s49, v[38:39]
	v_lshl_add_u64 v[18:19], v[18:19], 0, s[26:27]
	v_lshl_add_u64 v[18:19], v[18:19], 0, v[34:35]
	v_add_co_u32_e32 v22, vcc, s62, v18
	v_lshl_add_u64 v[24:25], v[24:25], 0, s[42:43]
	s_nop 0
	v_addc_co_u32_e32 v23, vcc, 0, v19, vcc
	global_load_dwordx2 v[22:23], v[22:23], off offset:1024
	v_cmp_gt_f32_e32 vcc, s63, v20
	s_waitcnt vmcnt(2)
	v_lshlrev_b32_e32 v30, 16, v26
	v_and_b32_e32 v31, 0xffff0000, v26
	v_lshlrev_b32_e32 v26, 16, v27
	v_and_b32_e32 v27, 0xffff0000, v27
	v_mul_f32_e32 v17, 0xbfb8aa3b, v30
	v_mul_f32_e32 v21, 0xbfb8aa3b, v31
	v_mul_f32_e32 v29, 0xbfb8aa3b, v26
	v_mul_f32_e32 v36, 0xbfb8aa3b, v27
	v_exp_f32_e32 v17, v17
	v_exp_f32_e32 v21, v21
	v_exp_f32_e32 v29, v29
	v_exp_f32_e32 v36, v36
	v_add_f32_e32 v17, 1.0, v17
	v_add_f32_e32 v21, 1.0, v21
	v_add_f32_e32 v29, 1.0, v29
	v_add_f32_e32 v39, 1.0, v36
	v_rcp_f32_e32 v36, v17
	v_rcp_f32_e32 v37, v21
	v_rcp_f32_e32 v38, v29
	v_rcp_f32_e32 v39, v39
	v_pk_mul_f32 v[8:9], v[8:9], v[28:29] op_sel_hi:[1,0]
	v_pk_mul_f32 v[10:11], v[10:11], v[28:29] op_sel_hi:[1,0]
	v_pk_mul_f32 v[28:29], v[36:37], v[30:31]
	v_pk_mul_f32 v[26:27], v[38:39], v[26:27]
	v_ashrrev_i32_e32 v17, 31, v16
	v_pk_mul_f32 v[10:11], v[242:243], v[10:11]
	v_pk_mul_f32 v[8:9], v[240:241], v[8:9]
	v_pk_mul_f32 v[10:11], v[10:11], v[26:27]
	v_pk_mul_f32 v[8:9], v[8:9], v[28:29]
	v_lshlrev_b64 v[12:13], 12, v[16:17]
	v_cvt_pk_bf16_f32 v8, v8, v9
	v_cvt_pk_bf16_f32 v9, v10, v11
	global_store_dwordx2 v[24:25], v[8:9], off offset:32
	v_mul_f32_e32 v16, 0x4b800000, v20
	v_cndmask_b32_e32 v16, v20, v16, vcc
	v_lshl_add_u64 v[14:15], v[18:19], 0, s[40:41]
	v_rsq_f32_e32 v18, v16
	global_load_dwordx2 v[14:15], v[14:15], off offset:32
	s_waitcnt vmcnt(2)
	v_lshlrev_b32_e32 v20, 16, v22
	v_and_b32_e32 v21, 0xffff0000, v22
	v_mul_f32_e32 v19, 0x45800000, v18
	v_lshlrev_b32_e32 v22, 16, v23
	v_and_b32_e32 v23, 0xffff0000, v23
	v_cndmask_b32_e32 v18, v18, v19, vcc
	v_mul_f32_e32 v19, 0xbfb8aa3b, v20
	v_mul_f32_e32 v24, 0xbfb8aa3b, v21
	v_mul_f32_e32 v25, 0xbfb8aa3b, v22
	v_mul_f32_e32 v26, 0xbfb8aa3b, v23
	v_exp_f32_e32 v19, v19
	v_exp_f32_e32 v24, v24
	v_exp_f32_e32 v25, v25
	v_exp_f32_e32 v26, v26
	v_add_f32_e32 v19, 1.0, v19
	v_add_f32_e32 v27, 1.0, v24
	v_add_f32_e32 v28, 1.0, v25
	v_add_f32_e32 v29, 1.0, v26
	v_rcp_f32_e32 v24, v19
	v_rcp_f32_e32 v25, v27
	v_rcp_f32_e32 v26, v28
	v_rcp_f32_e32 v27, v29
	v_lshl_add_u64 v[12:13], s[50:51], 0, v[12:13]
	v_lshl_add_u64 v[12:13], v[12:13], 0, s[26:27]
	v_pk_mul_f32 v[4:5], v[4:5], v[18:19] op_sel_hi:[1,0]
	v_pk_mul_f32 v[6:7], v[6:7], v[18:19] op_sel_hi:[1,0]
	v_lshl_add_u64 v[12:13], v[12:13], 0, v[34:35]
	v_pk_mul_f32 v[20:21], v[24:25], v[20:21]
	v_pk_mul_f32 v[22:23], v[26:27], v[22:23]
	v_add_co_u32_e64 v16, s[8:9], s88, v12
	v_pk_mul_f32 v[0:1], v[0:1], v[18:19] op_sel_hi:[1,0]
	s_nop 0
	v_addc_co_u32_e64 v17, s[8:9], 0, v13, s[8:9]
	v_pk_mul_f32 v[2:3], v[2:3], v[18:19] op_sel_hi:[1,0]
	v_pk_mul_f32 v[6:7], v[238:239], v[6:7]
	v_pk_mul_f32 v[4:5], v[236:237], v[4:5]
	v_pk_mul_f32 v[6:7], v[22:23], v[6:7]
	v_pk_mul_f32 v[4:5], v[20:21], v[4:5]
	v_lshl_add_u64 v[8:9], v[12:13], 0, s[42:43]
	v_cvt_pk_bf16_f32 v4, v4, v5
	v_cvt_pk_bf16_f32 v5, v6, v7
	global_store_dwordx2 v[16:17], v[4:5], off offset:2048
	s_waitcnt vmcnt(1)
	v_lshlrev_b32_e32 v10, 16, v14
	v_and_b32_e32 v11, 0xffff0000, v14
	v_lshlrev_b32_e32 v12, 16, v15
	v_and_b32_e32 v13, 0xffff0000, v15
	v_mul_f32_e32 v14, 0xbfb8aa3b, v10
	v_mul_f32_e32 v15, 0xbfb8aa3b, v11
	v_mul_f32_e32 v16, 0xbfb8aa3b, v12
	v_mul_f32_e32 v17, 0xbfb8aa3b, v13
	v_exp_f32_e32 v14, v14
	v_exp_f32_e32 v15, v15
	v_exp_f32_e32 v16, v16
	v_exp_f32_e32 v17, v17
	v_add_f32_e32 v14, 1.0, v14
	v_add_f32_e32 v15, 1.0, v15
	v_add_f32_e32 v16, 1.0, v16
	v_add_f32_e32 v17, 1.0, v17
	v_rcp_f32_e32 v14, v14
	v_rcp_f32_e32 v15, v15
	v_rcp_f32_e32 v16, v16
	v_rcp_f32_e32 v17, v17
	v_pk_mul_f32 v[10:11], v[14:15], v[10:11]
	v_pk_mul_f32 v[12:13], v[16:17], v[12:13]
	v_pk_mul_f32 v[2:3], v[242:243], v[2:3]
	v_pk_mul_f32 v[0:1], v[240:241], v[0:1]
	v_pk_mul_f32 v[2:3], v[2:3], v[12:13]
	v_pk_mul_f32 v[0:1], v[0:1], v[10:11]
	s_nop 0
	v_cvt_pk_bf16_f32 v0, v0, v1
	v_cvt_pk_bf16_f32 v1, v2, v3
	global_store_dwordx2 v[8:9], v[0:1], off offset:32
	s_barrier

; __device__ __forceinline__ unsigned pk2(float lo, float hi) { return pg8::cvt_pk_bf16(lo, hi); }
; __device__ __forceinline__ void b3_ssd_item(const Ctx& C, int li, int b, int c, int g) {
;     ...
;     { bf16* Y = (bf16*)(C.ws + WS_XN); const float* ng = C.in[9] + (size_t)li * 1024 + h * 64;
; #pragma unroll
;       for (int i = 0; i < 4; ++i) { float tot = 0.f;
; #pragma unroll
;           for (int k = 0; k < 8; ++k) tot += SSQ[k * 64 + 16 * i + fr];
;           const float rstd = rsqrtf(tot * (1.0f / 512.0f) + EPS);
; #pragma unroll
;           for (int j = 0; j < 4; ++j) { const f32x4 gn = *(const f32x4*)(ng + 16 * j + 4 * fq); const f32x4 y = acc[i][j] * rstd * gn;
;               *(v2u*)(Y + (size_t)(row0 + 16 * i + fr) * D + h * 64 + 16 * j + 4 * fq) = (v2u){pk2(y[0], y[1]), pk2(y[2], y[3])}; } } }
.LBB0_1890:
	s_or_b64 exec, exec, s[14:15]
	s_waitcnt lgkmcnt(0)
	s_barrier
	s_load_dwordx2 s[8:9], s[52:53], 0x48
	s_lshl_b64 s[10:11], s[12:13], 2
	v_lshlrev_b32_e32 v0, 2, v100
	v_mov_b32_e32 v1, v105
	v_lshl_add_u32 v72, v127, 2, 0
	s_waitcnt lgkmcnt(0)
	s_add_u32 s8, s8, s10
	s_addc_u32 s9, s9, s11
	v_lshl_add_u64 v[70:71], s[8:9], 0, v[0:1]
	v_add_co_u32_e32 v68, vcc, s78, v70
	v_add_u32_e32 v76, 0x22400, v72
	s_nop 0
	v_addc_co_u32_e32 v69, vcc, 0, v71, vcc
	global_load_dwordx4 v[236:239], v[68:69], off
	ds_read2_b32 v[72:73], v76 offset1:16
	ds_read2_b32 v[78:79], v76 offset0:64 offset1:80
	ds_read2_b32 v[80:81], v76 offset0:128 offset1:144
	ds_read2_b32 v[82:83], v76 offset0:192 offset1:208
	v_add_u32_e32 v77, 0x400, v76
	s_waitcnt lgkmcnt(3)
	v_mov_b32_e32 v92, v73
	v_mov_b32_e32 v93, v72
	s_waitcnt lgkmcnt(2)
	v_mov_b32_e32 v72, v79
	v_mov_b32_e32 v73, v78
	s_waitcnt lgkmcnt(1)
	v_mov_b32_e32 v78, v81
	v_mov_b32_e32 v79, v80
	s_waitcnt lgkmcnt(0)
	v_mov_b32_e32 v80, v83
	v_mov_b32_e32 v81, v82
	v_pk_add_f32 v[82:83], v[92:93], 0 op_sel_hi:[1,0]
	ds_read2_b32 v[84:85], v77 offset1:16
	ds_read2_b32 v[86:87], v77 offset0:64 offset1:80
	ds_read2_b32 v[88:89], v77 offset0:128 offset1:144
	ds_read2_b32 v[90:91], v77 offset0:192 offset1:208
	v_pk_add_f32 v[82:83], v[82:83], v[72:73]
	s_waitcnt lgkmcnt(3)
	v_mov_b32_e32 v92, v85
	v_pk_add_f32 v[78:79], v[82:83], v[78:79]
	v_mov_b32_e32 v93, v84
	v_pk_add_f32 v[78:79], v[78:79], v[80:81]
	s_waitcnt lgkmcnt(2)
	v_mov_b32_e32 v84, v87
	v_mov_b32_e32 v85, v86
	v_pk_add_f32 v[78:79], v[78:79], v[92:93]
	s_waitcnt lgkmcnt(1)
	v_mov_b32_e32 v86, v89
	v_mov_b32_e32 v87, v88
	v_pk_add_f32 v[78:79], v[78:79], v[84:85]
	s_waitcnt lgkmcnt(0)
	v_mov_b32_e32 v88, v91
	v_mov_b32_e32 v89, v90
	v_pk_add_f32 v[78:79], v[78:79], v[86:87]
	v_mov_b64_e32 v[74:75], s[38:39]
	v_pk_add_f32 v[78:79], v[78:79], v[88:89]
	s_lshl_b64 s[10:11], s[12:13], 1
	v_pk_fma_f32 v[78:79], v[78:79], s[36:37], v[74:75] op_sel_hi:[1,0,0]
	s_add_u32 s10, s50, s10
	v_mul_f32_e32 v80, 0x4b800000, v79
	v_cmp_gt_f32_e32 vcc, s63, v79
	s_addc_u32 s11, s51, s11
	v_lshl_add_u64 v[90:91], s[10:11], 0, v[104:105]
	v_cndmask_b32_e32 v79, v79, v80, vcc
	v_rsq_f32_e32 v79, v79
	v_lshlrev_b32_e32 v104, 12, v98
	s_mov_b64 s[8:9], 0x1000
	v_lshl_add_u64 v[72:73], v[90:91], 0, v[104:105]
	v_mul_f32_e32 v82, 0x45800000, v79
	v_cndmask_b32_e32 v82, v79, v82, vcc
	v_pk_mul_f32 v[8:9], v[8:9], v[82:83] op_sel_hi:[1,0]
	v_pk_mul_f32 v[10:11], v[10:11], v[82:83] op_sel_hi:[1,0]
	v_lshl_add_u64 v[70:71], v[70:71], 0, s[8:9]
	v_add_co_u32_e64 v80, s[8:9], s88, v72
	v_pk_mul_f32 v[4:5], v[4:5], v[82:83] op_sel_hi:[1,0]
	s_nop 0
	v_addc_co_u32_e64 v81, s[8:9], 0, v73, s[8:9]
	v_pk_mul_f32 v[6:7], v[6:7], v[82:83] op_sel_hi:[1,0]
	s_mov_b64 s[8:9], 0xe400000
	v_cmp_gt_f32_e32 vcc, s63, v78
	s_mov_b64 s[12:13], 0
	global_load_dwordx4 v[240:243], v[70:71], off offset:64
	global_load_dwordx4 v[244:247], v[70:71], off offset:128
	global_load_dwordx4 v[248:251], v[70:71], off offset:192
	s_waitcnt vmcnt(0)
	v_pk_mul_f32 v[2:3], v[238:239], v[10:11]
	v_pk_mul_f32 v[0:1], v[236:237], v[8:9]
	v_lshl_add_u64 v[8:9], v[72:73], 0, s[8:9]
	v_cvt_pk_bf16_f32 v0, v0, v1
	v_cvt_pk_bf16_f32 v1, v2, v3
	global_store_dwordx2 v[80:81], v[0:1], off
	s_mov_b32 s8, 0xe410000
	v_pk_mul_f32 v[2:3], v[242:243], v[6:7]
	v_pk_mul_f32 v[0:1], v[240:241], v[4:5]
	v_pk_mul_f32 v[4:5], v[16:17], v[82:83] op_sel_hi:[1,0]
	v_cvt_pk_bf16_f32 v0, v0, v1
	v_cvt_pk_bf16_f32 v1, v2, v3
	global_store_dwordx2 v[8:9], v[0:1], off offset:32
	v_pk_mul_f32 v[6:7], v[18:19], v[82:83] op_sel_hi:[1,0]
	v_pk_mul_f32 v[0:1], v[244:245], v[4:5]
	v_pk_mul_f32 v[2:3], v[246:247], v[6:7]
	v_cvt_pk_bf16_f32 v0, v0, v1
	v_cvt_pk_bf16_f32 v1, v2, v3
	global_store_dwordx2 v[8:9], v[0:1], off offset:64
	v_pk_mul_f32 v[4:5], v[20:21], v[82:83] op_sel_hi:[1,0]
	v_pk_mul_f32 v[6:7], v[22:23], v[82:83] op_sel_hi:[1,0]
	v_pk_mul_f32 v[0:1], v[248:249], v[4:5]
	v_pk_mul_f32 v[2:3], v[250:251], v[6:7]
	v_cvt_pk_bf16_f32 v0, v0, v1
	v_cvt_pk_bf16_f32 v1, v2, v3
	global_store_dwordx2 v[8:9], v[0:1], off offset:96
	v_mul_f32_e32 v4, 0x4b800000, v78
	v_cndmask_b32_e32 v4, v78, v4, vcc
	v_rsq_f32_e32 v6, v4
	v_add_co_u32_e64 v4, s[8:9], s8, v72
	v_mul_f32_e32 v7, 0x45800000, v6
	v_cndmask_b32_e32 v6, v6, v7, vcc
	v_pk_mul_f32 v[8:9], v[40:41], v[6:7] op_sel_hi:[1,0]
	v_pk_mul_f32 v[10:11], v[42:43], v[6:7] op_sel_hi:[1,0]
	v_addc_co_u32_e64 v5, s[8:9], 0, v73, s[8:9]
	s_mov_b32 s8, 0xe420000
	v_pk_mul_f32 v[2:3], v[238:239], v[10:11]
	v_pk_mul_f32 v[0:1], v[236:237], v[8:9]
	v_pk_mul_f32 v[8:9], v[36:37], v[6:7] op_sel_hi:[1,0]
	v_cvt_pk_bf16_f32 v0, v0, v1
	v_cvt_pk_bf16_f32 v1, v2, v3
	global_store_dwordx2 v[4:5], v[0:1], off
	v_pk_mul_f32 v[10:11], v[38:39], v[6:7] op_sel_hi:[1,0]
	v_pk_mul_f32 v[0:1], v[240:241], v[8:9]
	v_pk_mul_f32 v[2:3], v[242:243], v[10:11]
	v_cvt_pk_bf16_f32 v0, v0, v1
	v_cvt_pk_bf16_f32 v1, v2, v3
	global_store_dwordx2 v[4:5], v[0:1], off offset:32
	v_pk_mul_f32 v[8:9], v[28:29], v[6:7] op_sel_hi:[1,0]
	v_pk_mul_f32 v[10:11], v[30:31], v[6:7] op_sel_hi:[1,0]
	v_pk_mul_f32 v[0:1], v[244:245], v[8:9]
	v_pk_mul_f32 v[2:3], v[246:247], v[10:11]
	v_cvt_pk_bf16_f32 v0, v0, v1
	v_cvt_pk_bf16_f32 v1, v2, v3
	global_store_dwordx2 v[4:5], v[0:1], off offset:64
	v_pk_mul_f32 v[8:9], v[44:45], v[6:7] op_sel_hi:[1,0]
	v_pk_mul_f32 v[6:7], v[46:47], v[6:7] op_sel_hi:[1,0]
	v_pk_mul_f32 v[0:1], v[248:249], v[8:9]
	v_pk_mul_f32 v[2:3], v[250:251], v[6:7]
	v_cvt_pk_bf16_f32 v0, v0, v1
	v_cvt_pk_bf16_f32 v1, v2, v3
	global_store_dwordx2 v[4:5], v[0:1], off offset:96
	ds_read2_b32 v[4:5], v76 offset0:32 offset1:48
	ds_read2_b32 v[6:7], v76 offset0:96 offset1:112
	ds_read2_b32 v[8:9], v76 offset0:160 offset1:176
	ds_read2_b32 v[10:11], v76 offset0:224 offset1:240
	ds_read2_b32 v[16:17], v77 offset0:32 offset1:48
	ds_read2_b32 v[18:19], v77 offset0:96 offset1:112
	ds_read2_b32 v[20:21], v77 offset0:160 offset1:176
	ds_read2_b32 v[22:23], v77 offset0:224 offset1:240
	s_waitcnt lgkmcnt(7)
; __device__ __forceinline__ unsigned pk2(float lo, float hi) { return pg8::cvt_pk_bf16(lo, hi); }
; __device__ __forceinline__ void b3_ssd_item(const Ctx& C, int li, int b, int c, int g) {
;     ...
;       for (int i = 0; i < 4; ++i) { float tot = 0.f;
; #pragma unroll
;           for (int k = 0; k < 8; ++k) tot += SSQ[k * 64 + 16 * i + fr];
;           const float rstd = rsqrtf(tot * (1.0f / 512.0f) + EPS);
; #pragma unroll
;           for (int j = 0; j < 4; ++j) { const f32x4 gn = *(const f32x4*)(ng + 16 * j + 4 * fq); const f32x4 y = acc[i][j] * rstd * gn;
;               *(v2u*)(Y + (size_t)(row0 + 16 * i + fr) * D + h * 64 + 16 * j + 4 * fq) = (v2u){pk2(y[0], y[1]), pk2(y[2], y[3])}; } } }
	v_mov_b32_e32 v28, v5
	v_mov_b32_e32 v29, v4
	s_waitcnt lgkmcnt(6)
	v_mov_b32_e32 v4, v7
	v_mov_b32_e32 v5, v6
	s_waitcnt lgkmcnt(5)
	v_mov_b32_e32 v6, v9
	v_mov_b32_e32 v7, v8
	s_waitcnt lgkmcnt(4)
	v_mov_b32_e32 v8, v11
	v_mov_b32_e32 v9, v10
	v_pk_add_f32 v[10:11], v[28:29], 0 op_sel_hi:[1,0]
	s_waitcnt lgkmcnt(3)
	v_mov_b32_e32 v28, v17
	v_pk_add_f32 v[4:5], v[10:11], v[4:5]
	v_mov_b32_e32 v29, v16
	v_pk_add_f32 v[4:5], v[4:5], v[6:7]
	s_waitcnt lgkmcnt(2)
	v_mov_b32_e32 v16, v19
	v_pk_add_f32 v[4:5], v[4:5], v[8:9]
	v_mov_b32_e32 v17, v18
	v_pk_add_f32 v[4:5], v[4:5], v[28:29]
	s_waitcnt lgkmcnt(1)
	v_mov_b32_e32 v18, v21
	v_mov_b32_e32 v19, v20
	v_pk_add_f32 v[4:5], v[4:5], v[16:17]
	s_waitcnt lgkmcnt(0)
	v_mov_b32_e32 v20, v23
	v_mov_b32_e32 v21, v22
	v_pk_add_f32 v[4:5], v[4:5], v[18:19]
	s_nop 0
	v_pk_add_f32 v[4:5], v[4:5], v[20:21]
	s_nop 0
	v_pk_fma_f32 v[4:5], v[4:5], s[36:37], v[74:75] op_sel_hi:[1,0,0]
	s_nop 0
	v_mul_f32_e32 v6, 0x4b800000, v5
	v_cmp_gt_f32_e32 vcc, s63, v5
	s_nop 1
	v_cndmask_b32_e32 v5, v5, v6, vcc
	v_rsq_f32_e32 v5, v5
	v_add_co_u32_e64 v6, s[8:9], s8, v72
	v_mul_f32_e32 v8, 0x45800000, v5
	v_cndmask_b32_e32 v8, v5, v8, vcc
	v_pk_mul_f32 v[10:11], v[56:57], v[8:9] op_sel_hi:[1,0]
	v_pk_mul_f32 v[16:17], v[58:59], v[8:9] op_sel_hi:[1,0]
	v_addc_co_u32_e64 v7, s[8:9], 0, v73, s[8:9]
	v_mul_f32_e32 v5, 0x4b800000, v4
	v_cmp_gt_f32_e32 vcc, s63, v4
	s_mov_b32 s8, 0xe430000
	v_pk_mul_f32 v[2:3], v[238:239], v[16:17]
	v_pk_mul_f32 v[0:1], v[236:237], v[10:11]
	v_pk_mul_f32 v[10:11], v[52:53], v[8:9] op_sel_hi:[1,0]
	v_cvt_pk_bf16_f32 v0, v0, v1
	v_cvt_pk_bf16_f32 v1, v2, v3
	global_store_dwordx2 v[6:7], v[0:1], off
	v_pk_mul_f32 v[16:17], v[54:55], v[8:9] op_sel_hi:[1,0]
	v_cndmask_b32_e32 v4, v4, v5, vcc
	v_pk_mul_f32 v[2:3], v[242:243], v[16:17]
	v_pk_mul_f32 v[0:1], v[240:241], v[10:11]
	v_pk_mul_f32 v[10:11], v[48:49], v[8:9] op_sel_hi:[1,0]
	v_cvt_pk_bf16_f32 v0, v0, v1
	v_cvt_pk_bf16_f32 v1, v2, v3
	global_store_dwordx2 v[6:7], v[0:1], off offset:32
	v_pk_mul_f32 v[16:17], v[50:51], v[8:9] op_sel_hi:[1,0]
	v_pk_mul_f32 v[0:1], v[244:245], v[10:11]
	v_pk_mul_f32 v[2:3], v[246:247], v[16:17]
	v_cvt_pk_bf16_f32 v0, v0, v1
	v_cvt_pk_bf16_f32 v1, v2, v3
	global_store_dwordx2 v[6:7], v[0:1], off offset:64
	v_pk_mul_f32 v[10:11], v[60:61], v[8:9] op_sel_hi:[1,0]
	v_pk_mul_f32 v[8:9], v[62:63], v[8:9] op_sel_hi:[1,0]
	v_pk_mul_f32 v[0:1], v[248:249], v[10:11]
	v_pk_mul_f32 v[2:3], v[250:251], v[8:9]
	v_cvt_pk_bf16_f32 v0, v0, v1
	v_cvt_pk_bf16_f32 v1, v2, v3
	global_store_dwordx2 v[6:7], v[0:1], off offset:96
	v_rsq_f32_e32 v6, v4
	v_add_co_u32_e64 v4, s[8:9], s8, v72
	v_mul_f32_e32 v7, 0x45800000, v6
	v_cndmask_b32_e32 v6, v6, v7, vcc
	v_pk_mul_f32 v[8:9], v[32:33], v[6:7] op_sel_hi:[1,0]
	v_pk_mul_f32 v[10:11], v[34:35], v[6:7] op_sel_hi:[1,0]
	v_addc_co_u32_e64 v5, s[8:9], 0, v73, s[8:9]
	v_pk_mul_f32 v[2:3], v[238:239], v[10:11]
	v_pk_mul_f32 v[0:1], v[236:237], v[8:9]
	v_pk_mul_f32 v[8:9], v[24:25], v[6:7] op_sel_hi:[1,0]
	v_cvt_pk_bf16_f32 v0, v0, v1
	v_cvt_pk_bf16_f32 v1, v2, v3
	global_store_dwordx2 v[4:5], v[0:1], off
	v_pk_mul_f32 v[10:11], v[26:27], v[6:7] op_sel_hi:[1,0]
	v_pk_mul_f32 v[0:1], v[240:241], v[8:9]
	v_pk_mul_f32 v[2:3], v[242:243], v[10:11]
	v_cvt_pk_bf16_f32 v0, v0, v1
	v_cvt_pk_bf16_f32 v1, v2, v3
	global_store_dwordx2 v[4:5], v[0:1], off offset:32
	v_pk_mul_f32 v[8:9], v[12:13], v[6:7] op_sel_hi:[1,0]
	v_pk_mul_f32 v[10:11], v[14:15], v[6:7] op_sel_hi:[1,0]
	v_pk_mul_f32 v[0:1], v[244:245], v[8:9]
	v_pk_mul_f32 v[2:3], v[246:247], v[10:11]
	v_cvt_pk_bf16_f32 v0, v0, v1
	v_cvt_pk_bf16_f32 v1, v2, v3
	global_store_dwordx2 v[4:5], v[0:1], off offset:64
	v_pk_mul_f32 v[8:9], v[64:65], v[6:7] op_sel_hi:[1,0]
	v_pk_mul_f32 v[6:7], v[66:67], v[6:7] op_sel_hi:[1,0]
	v_pk_mul_f32 v[0:1], v[248:249], v[8:9]
	v_pk_mul_f32 v[2:3], v[250:251], v[6:7]
	v_cvt_pk_bf16_f32 v0, v0, v1
	v_cvt_pk_bf16_f32 v1, v2, v3
	global_store_dwordx2 v[4:5], v[0:1], off offset:96
	s_barrier
